# conv epilogue: dead DPP old-value inits removed, ACT dwordx2 store pairs merged to dwordx4, counted wait after HALO stores; fixup HALO loads hoisted
# speedup vs baseline: 1.0154x; 1.0124x over previous
;     __device__ __forceinline__ void operator()(const f32x4 (&acc)[2][2][4][2], const Unit& u, int wr, int wc, int fr, int fq) const {
;     ...
;             for (int ai = 0; ai < 2; ++ai) {
;                 __builtin_amdgcn_sched_barrier(0);
;                 const int jc = j0 + 4 * n;
;                 f32x2 o[4][2];
; #pragma unroll
;                 for (int xp = 0; xp < 2; ++xp) {
;                     const f32x2 a0 = (f32x2){wg[n][0][2 * xp], wg[n][0][2 * xp + 1]}, a1 = (f32x2){wg[n][1][2 * xp], wg[n][1][2 * xp + 1]}, a2 = (f32x2){wg[n][2][2 * xp], wg[n][2][2 * xp + 1]};
;                     const f32x2 b0 = (f32x2){wv[n][0][2 * xp], wv[n][0][2 * xp + 1]}, b1 = (f32x2){wv[n][1][2 * xp], wv[n][1][2 * xp + 1]}, b2 = (f32x2){wv[n][2][2 * xp], wv[n][2][2 * xp + 1]};
;                     f32x2 g1p = (f32x2){0.f, 0.f}, g2p = g1p, v1p = g1p, v2p = g1p;
; #pragma unroll
;                     for (int m = 0; m < 4; ++m) {
;                         const f32x2 g = (f32x2){acc[ai][0][m][n][2 * xp], acc[ai][0][m][n][2 * xp + 1]}, v = (f32x2){acc[ai][1][m][n][2 * xp], acc[ai][1][m][n][2 * xp + 1]};
;                         f32x2 g1, g2, v1, v2, ga, gb, va, vb;
; #pragma unroll
;                         for (int c = 0; c < 2; ++c) { g1[c] = dpp_ror<0x121>(g[c]); g2[c] = dpp_ror<0x122>(g[c]); v1[c] = dpp_ror<0x121>(v[c]); v2[c] = dpp_ror<0x122>(v[c]);
;                             ga[c] = fr == 0 ? g1p[c] : g1[c]; gb[c] = fr < 2 ? g2p[c] : g2[c]; va[c] = fr == 0 ? v1p[c] : v1[c]; vb[c] = fr < 2 ? v2p[c] : v2[c]; }
;                         const f32x2 G = a0 * gb + a1 * ga + a2 * g, V = b0 * vb + b1 * va + b2 * v;
;                         const f32x2 t = G * (-1.4426950408889634f);
;                         f32x2 e; e.x = __builtin_amdgcn_exp2f(t.x); e.y = __builtin_amdgcn_exp2f(t.y);
;                         const f32x2 dn = e + 1.0f;
;                         f32x2 rc; rc.x = __builtin_amdgcn_rcpf(dn.x); rc.y = __builtin_amdgcn_rcpf(dn.y);
;                         o[m][xp] = (G * rc) * V;
;                         g1p = g1; g2p = g2; v1p = v1; v2p = v2;
;                     }
;                 }
; #pragma unroll
;                 for (int m = 0; m < 4; ++m) { const int row = u.pm * BM + ai * HALF + wr * 64 + m * 16 + fr;
;                     u32x2 w; w.x = cvt_pk_bf16(o[m][0].x, o[m][0].y); w.y = cvt_pk_bf16(o[m][1].x, o[m][1].y);
.LBB0_676:
	s_or_b64 exec, exec, s[56:57]
	v_lshl_add_u32 v183, s52, 8, v177
	v_mov_b32_dpp v210, v144 row_ror:2 row_mask:0xf bank_mask:0xf
	s_nop 0
	v_mov_b32_dpp v218, v145 row_ror:2 row_mask:0xf bank_mask:0xf
	v_mov_b32_dpp v208, v144 row_ror:1 row_mask:0xf bank_mask:0xf
	v_cndmask_b32_e64 v192, v210, 0, s[6:7]
	v_mov_b32_dpp v220, v145 row_ror:1 row_mask:0xf bank_mask:0xf
	v_cndmask_b32_e64 v193, v218, 0, s[6:7]
	v_cndmask_b32_e64 v190, v208, 0, s[8:9]
	v_cndmask_b32_e64 v191, v220, 0, s[8:9]
	s_waitcnt vmcnt(4)
	v_pk_mul_f32 v[192:193], v[132:133], v[192:193]
	s_nop 0
	v_pk_fma_f32 v[190:191], v[136:137], v[190:191], v[192:193]
	s_nop 0
	v_pk_fma_f32 v[144:145], v[144:145], v[140:141], v[190:191]
	s_nop 0
	v_pk_mul_f32 v[190:191], v[144:145], s[40:41] op_sel_hi:[1,0]
	v_mov_b32_dpp v211, v146 row_ror:2 row_mask:0xf bank_mask:0xf
	s_nop 0
	v_mov_b32_dpp v219, v147 row_ror:2 row_mask:0xf bank_mask:0xf
	v_exp_f32_e32 v190, v190
	v_exp_f32_e32 v191, v191
	v_mov_b32_dpp v209, v146 row_ror:1 row_mask:0xf bank_mask:0xf
	v_cndmask_b32_e64 v202, v211, 0, s[6:7]
	v_mov_b32_dpp v222, v147 row_ror:1 row_mask:0xf bank_mask:0xf
	v_cndmask_b32_e64 v203, v219, 0, s[6:7]
	v_cndmask_b32_e64 v198, v209, 0, s[8:9]
	v_cndmask_b32_e64 v199, v222, 0, s[8:9]
	v_pk_mul_f32 v[202:203], v[134:135], v[202:203]
	v_pk_add_f32 v[190:191], v[190:191], 1.0 op_sel_hi:[1,0]
	v_pk_fma_f32 v[198:199], v[138:139], v[198:199], v[202:203]
	v_rcp_f32_e32 v190, v190
	v_pk_fma_f32 v[146:147], v[146:147], v[142:143], v[198:199]
	v_rcp_f32_e32 v191, v191
	v_pk_mul_f32 v[198:199], v[146:147], s[40:41] op_sel_hi:[1,0]
	s_nop 0
	v_exp_f32_e32 v198, v198
	v_exp_f32_e32 v199, v199
	v_pk_mul_f32 v[144:145], v[144:145], v[190:191]
	s_nop 0
	s_nop 0
	v_pk_add_f32 v[198:199], v[198:199], 1.0 op_sel_hi:[1,0]
	v_mov_b32_dpp v185, v148 row_ror:2 row_mask:0xf bank_mask:0xf
	v_mov_b32_dpp v189, v149 row_ror:2 row_mask:0xf bank_mask:0xf
	v_mov_b32_dpp v186, v150 row_ror:2 row_mask:0xf bank_mask:0xf
	v_mov_b32_dpp v191, v151 row_ror:2 row_mask:0xf bank_mask:0xf
	v_rcp_f32_e32 v198, v198
	v_rcp_f32_e32 v199, v199
	v_mov_b32_dpp v212, v148 row_ror:1 row_mask:0xf bank_mask:0xf
	v_cndmask_b32_e64 v196, v185, 0, s[6:7]
	v_mov_b32_dpp v187, v149 row_ror:1 row_mask:0xf bank_mask:0xf
	v_cndmask_b32_e64 v197, v189, 0, s[6:7]
	v_mov_b32_dpp v214, v150 row_ror:1 row_mask:0xf bank_mask:0xf
	v_cndmask_b32_e64 v244, v186, 0, s[6:7]
	v_mov_b32_dpp v190, v151 row_ror:1 row_mask:0xf bank_mask:0xf
	v_cndmask_b32_e64 v245, v191, 0, s[6:7]
	v_cndmask_b32_e64 v194, v212, 0, s[8:9]
	v_cndmask_b32_e64 v195, v187, 0, s[8:9]
	v_pk_mul_f32 v[192:193], v[120:121], v[196:197]
	v_cndmask_b32_e64 v242, v214, 0, s[8:9]
	v_cndmask_b32_e64 v243, v190, 0, s[8:9]
	v_pk_mul_f32 v[202:203], v[122:123], v[244:245]
	v_pk_fma_f32 v[192:193], v[124:125], v[194:195], v[192:193]
	v_pk_fma_f32 v[202:203], v[126:127], v[242:243], v[202:203]
	v_pk_fma_f32 v[148:149], v[148:149], v[128:129], v[192:193]
	v_pk_fma_f32 v[150:151], v[150:151], v[130:131], v[202:203]
	v_pk_mul_f32 v[146:147], v[146:147], v[198:199]
	v_pk_mul_f32 v[144:145], v[148:149], v[144:145]
	s_nop 0
	s_nop 0
	s_nop 0
	v_pk_mul_f32 v[242:243], v[150:151], v[146:147]
	s_nop 0
	s_nop 0
	s_nop 0
	v_mov_b32_dpp v232, v116 row_ror:1 row_mask:0xf bank_mask:0xf
	v_mov_b32_dpp v234, v116 row_ror:2 row_mask:0xf bank_mask:0xf
	v_mov_b32_dpp v236, v112 row_ror:1 row_mask:0xf bank_mask:0xf
	v_mov_b32_dpp v206, v112 row_ror:2 row_mask:0xf bank_mask:0xf
	v_mov_b32_dpp v240, v117 row_ror:1 row_mask:0xf bank_mask:0xf
	v_mov_b32_dpp v238, v117 row_ror:2 row_mask:0xf bank_mask:0xf
	v_mov_b32_dpp v213, v113 row_ror:1 row_mask:0xf bank_mask:0xf
	v_mov_b32_dpp v216, v113 row_ror:2 row_mask:0xf bank_mask:0xf
	v_mov_b32_dpp v192, v108 row_ror:1 row_mask:0xf bank_mask:0xf
	v_mov_b32_dpp v194, v108 row_ror:2 row_mask:0xf bank_mask:0xf
	v_mov_b32_dpp v196, v104 row_ror:1 row_mask:0xf bank_mask:0xf
	v_mov_b32_dpp v148, v104 row_ror:2 row_mask:0xf bank_mask:0xf
	v_mov_b32_dpp v204, v109 row_ror:1 row_mask:0xf bank_mask:0xf
	v_mov_b32_dpp v200, v109 row_ror:2 row_mask:0xf bank_mask:0xf
	v_mov_b32_dpp v149, v105 row_ror:1 row_mask:0xf bank_mask:0xf
	v_mov_b32_dpp v184, v105 row_ror:2 row_mask:0xf bank_mask:0xf
	v_mov_b32_dpp v221, v96 row_ror:1 row_mask:0xf bank_mask:0xf
	v_mov_b32_dpp v224, v96 row_ror:2 row_mask:0xf bank_mask:0xf
	v_mov_b32_dpp v226, v100 row_ror:1 row_mask:0xf bank_mask:0xf
	v_mov_b32_dpp v188, v100 row_ror:2 row_mask:0xf bank_mask:0xf
	v_mov_b32_dpp v230, v97 row_ror:1 row_mask:0xf bank_mask:0xf
	v_mov_b32_dpp v228, v97 row_ror:2 row_mask:0xf bank_mask:0xf
	v_mov_b32_dpp v197, v101 row_ror:1 row_mask:0xf bank_mask:0xf
	v_mov_b32_dpp v201, v101 row_ror:2 row_mask:0xf bank_mask:0xf
	v_mov_b32_dpp v233, v118 row_ror:1 row_mask:0xf bank_mask:0xf
	v_mov_b32_dpp v235, v118 row_ror:2 row_mask:0xf bank_mask:0xf
	v_mov_b32_dpp v237, v114 row_ror:1 row_mask:0xf bank_mask:0xf
	v_mov_b32_dpp v207, v114 row_ror:2 row_mask:0xf bank_mask:0xf
	v_mov_b32_dpp v241, v119 row_ror:1 row_mask:0xf bank_mask:0xf
	v_mov_b32_dpp v239, v119 row_ror:2 row_mask:0xf bank_mask:0xf
	v_mov_b32_dpp v215, v115 row_ror:1 row_mask:0xf bank_mask:0xf
	v_mov_b32_dpp v217, v115 row_ror:2 row_mask:0xf bank_mask:0xf
	v_mov_b32_dpp v193, v110 row_ror:1 row_mask:0xf bank_mask:0xf
	v_mov_b32_dpp v195, v110 row_ror:2 row_mask:0xf bank_mask:0xf
	v_mov_b32_dpp v198, v106 row_ror:1 row_mask:0xf bank_mask:0xf
	v_mov_b32_dpp v146, v106 row_ror:2 row_mask:0xf bank_mask:0xf
	v_mov_b32_dpp v205, v111 row_ror:1 row_mask:0xf bank_mask:0xf
	v_mov_b32_dpp v202, v111 row_ror:2 row_mask:0xf bank_mask:0xf
	v_mov_b32_dpp v147, v107 row_ror:1 row_mask:0xf bank_mask:0xf
	v_mov_b32_dpp v150, v107 row_ror:2 row_mask:0xf bank_mask:0xf
	v_mov_b32_dpp v223, v98 row_ror:1 row_mask:0xf bank_mask:0xf
	v_mov_b32_dpp v225, v98 row_ror:2 row_mask:0xf bank_mask:0xf
	v_mov_b32_dpp v227, v102 row_ror:1 row_mask:0xf bank_mask:0xf
	v_mov_b32_dpp v151, v102 row_ror:2 row_mask:0xf bank_mask:0xf
	v_mov_b32_dpp v231, v99 row_ror:1 row_mask:0xf bank_mask:0xf
	v_mov_b32_dpp v229, v99 row_ror:2 row_mask:0xf bank_mask:0xf
	v_mov_b32_dpp v199, v103 row_ror:1 row_mask:0xf bank_mask:0xf
	v_mov_b32_dpp v203, v103 row_ror:2 row_mask:0xf bank_mask:0xf
	v_cvt_pk_bf16_f32 v144, v144, v145
	v_cvt_pk_bf16_f32 v145, v242, v243
	s_and_saveexec_b64 s[52:53], s[10:11]
	s_cbranch_execz .LBB0_678
	v_mov_b64_e32 v[242:243], s[18:19]
	v_mad_i64_i32 v[242:243], s[44:45], v183, s92, v[242:243]
	v_lshl_add_u64 v[242:243], v[170:171], 1, v[242:243]
	global_store_dwordx2 v[242:243], v[144:145], off
; template <int CTRL> __device__ __forceinline__ float dpp_ror(float v) { return __builtin_bit_cast(float, __builtin_amdgcn_update_dpp(0, __builtin_bit_cast(int, v), CTRL, 0xf, 0xf, false)); }
;     __device__ __forceinline__ void operator()(const f32x4 (&acc)[2][2][4][2], const Unit& u, int wr, int wc, int fr, int fq) const {
;     ...
;                     for (int m = 0; m < 4; ++m) {
;                         const f32x2 g = (f32x2){acc[ai][0][m][n][2 * xp], acc[ai][0][m][n][2 * xp + 1]}, v = (f32x2){acc[ai][1][m][n][2 * xp], acc[ai][1][m][n][2 * xp + 1]};
;                         f32x2 g1, g2, v1, v2, ga, gb, va, vb;
; #pragma unroll
;                         for (int c = 0; c < 2; ++c) { g1[c] = dpp_ror<0x121>(g[c]); g2[c] = dpp_ror<0x122>(g[c]); v1[c] = dpp_ror<0x121>(v[c]); v2[c] = dpp_ror<0x122>(v[c]);
;                             ga[c] = fr == 0 ? g1p[c] : g1[c]; gb[c] = fr < 2 ? g2p[c] : g2[c]; va[c] = fr == 0 ? v1p[c] : v1[c]; vb[c] = fr < 2 ? v2p[c] : v2[c]; }
;                         const f32x2 G = a0 * gb + a1 * ga + a2 * g, V = b0 * vb + b1 * va + b2 * v;
;                         const f32x2 t = G * (-1.4426950408889634f);
;                         f32x2 e; e.x = __builtin_amdgcn_exp2f(t.x); e.y = __builtin_amdgcn_exp2f(t.y);
;                         const f32x2 dn = e + 1.0f;
;                         f32x2 rc; rc.x = __builtin_amdgcn_rcpf(dn.x); rc.y = __builtin_amdgcn_rcpf(dn.y);
;                         o[m][xp] = (G * rc) * V;
;                         g1p = g1; g2p = g2; v1p = v1; v2p = v2;
.LBB0_678:
	s_or_b64 exec, exec, s[52:53]
	v_cndmask_b32_e64 v242, v234, v210, s[6:7]
	v_cndmask_b32_e64 v243, v238, v218, s[6:7]
	v_cndmask_b32_e64 v144, v232, v208, s[8:9]
	v_cndmask_b32_e64 v145, v240, v220, s[8:9]
	v_pk_mul_f32 v[242:243], v[132:133], v[242:243]
	v_cndmask_b32_e64 v244, v236, v212, s[8:9]
	v_pk_fma_f32 v[144:145], v[136:137], v[144:145], v[242:243]
	v_cndmask_b32_e64 v242, v206, v185, s[6:7]
	v_pk_fma_f32 v[116:117], v[116:117], v[140:141], v[144:145]
	v_cndmask_b32_e64 v243, v216, v189, s[6:7]
	v_pk_mul_f32 v[144:145], v[116:117], s[40:41] op_sel_hi:[1,0]
	v_cndmask_b32_e64 v245, v213, v187, s[8:9]
	v_exp_f32_e32 v144, v144
	v_exp_f32_e32 v145, v145
	v_pk_mul_f32 v[242:243], v[120:121], v[242:243]
	v_cndmask_b32_e64 v212, v196, v236, s[8:9]
	v_pk_fma_f32 v[242:243], v[124:125], v[244:245], v[242:243]
	v_pk_add_f32 v[144:145], v[144:145], 1.0 op_sel_hi:[1,0]
	v_pk_fma_f32 v[112:113], v[112:113], v[128:129], v[242:243]
	v_rcp_f32_e32 v144, v144
	v_rcp_f32_e32 v145, v145
	v_cndmask_b32_e64 v213, v149, v213, s[8:9]
	v_pk_mul_f32 v[116:117], v[116:117], v[144:145]
	v_cndmask_b32_e64 v144, v194, v234, s[6:7]
	v_cndmask_b32_e64 v145, v200, v238, s[6:7]
	v_pk_mul_f32 v[112:113], v[112:113], v[116:117]
	v_cndmask_b32_e64 v116, v192, v232, s[8:9]
	v_cndmask_b32_e64 v117, v204, v240, s[8:9]
	v_pk_mul_f32 v[144:145], v[132:133], v[144:145]
	s_nop 0
	v_pk_fma_f32 v[116:117], v[136:137], v[116:117], v[144:145]
	v_cndmask_b32_e64 v144, v148, v206, s[6:7]
	v_pk_fma_f32 v[108:109], v[108:109], v[140:141], v[116:117]
	v_cndmask_b32_e64 v145, v184, v216, s[6:7]
	v_pk_mul_f32 v[116:117], v[108:109], s[40:41] op_sel_hi:[1,0]
	v_pk_mul_f32 v[144:145], v[120:121], v[144:145]
	v_exp_f32_e32 v116, v116
	v_exp_f32_e32 v117, v117
	v_pk_fma_f32 v[144:145], v[124:125], v[212:213], v[144:145]
	v_pk_add_f32 v[116:117], v[116:117], 1.0 op_sel_hi:[1,0]
	s_nop 0
	v_rcp_f32_e32 v116, v116
	v_rcp_f32_e32 v117, v117
	v_pk_fma_f32 v[104:105], v[104:105], v[128:129], v[144:145]
	v_cndmask_b32_e64 v144, v226, v196, s[8:9]
	v_cndmask_b32_e64 v145, v197, v149, s[8:9]
	v_pk_mul_f32 v[108:109], v[108:109], v[116:117]
	v_cndmask_b32_e64 v116, v224, v194, s[6:7]
	v_cndmask_b32_e64 v117, v228, v200, s[6:7]
	v_pk_mul_f32 v[104:105], v[104:105], v[108:109]
	v_cndmask_b32_e64 v108, v221, v192, s[8:9]
	v_cndmask_b32_e64 v109, v230, v204, s[8:9]
	v_pk_mul_f32 v[116:117], v[132:133], v[116:117]
	s_nop 0
	v_pk_fma_f32 v[108:109], v[136:137], v[108:109], v[116:117]
	v_cndmask_b32_e64 v116, v188, v148, s[6:7]
	v_pk_fma_f32 v[96:97], v[96:97], v[140:141], v[108:109]
	v_cndmask_b32_e64 v117, v201, v184, s[6:7]
	v_pk_mul_f32 v[108:109], v[96:97], s[40:41] op_sel_hi:[1,0]
	v_pk_mul_f32 v[116:117], v[120:121], v[116:117]
	v_exp_f32_e32 v108, v108
	v_exp_f32_e32 v109, v109
	v_pk_fma_f32 v[116:117], v[124:125], v[144:145], v[116:117]
	v_pk_add_f32 v[108:109], v[108:109], 1.0 op_sel_hi:[1,0]
	s_nop 0
	v_rcp_f32_e32 v108, v108
	v_rcp_f32_e32 v109, v109
	v_pk_fma_f32 v[100:101], v[100:101], v[128:129], v[116:117]
	v_cndmask_b32_e64 v116, v237, v214, s[8:9]
	v_cndmask_b32_e64 v117, v215, v190, s[8:9]
	v_pk_mul_f32 v[96:97], v[96:97], v[108:109]
	v_cndmask_b32_e64 v108, v235, v211, s[6:7]
	v_cndmask_b32_e64 v109, v239, v219, s[6:7]
	v_pk_mul_f32 v[100:101], v[100:101], v[96:97]
	v_cndmask_b32_e64 v96, v233, v209, s[8:9]
	v_cndmask_b32_e64 v97, v241, v222, s[8:9]
	v_pk_mul_f32 v[108:109], v[134:135], v[108:109]
	s_nop 0
	v_pk_fma_f32 v[96:97], v[138:139], v[96:97], v[108:109]
	s_nop 0
	v_pk_fma_f32 v[96:97], v[118:119], v[142:143], v[96:97]
	v_cndmask_b32_e64 v118, v207, v186, s[6:7]
	v_pk_mul_f32 v[108:109], v[96:97], s[40:41] op_sel_hi:[1,0]
	v_cndmask_b32_e64 v119, v217, v191, s[6:7]
	v_exp_f32_e32 v108, v108
	v_exp_f32_e32 v109, v109
	v_pk_mul_f32 v[118:119], v[122:123], v[118:119]
	v_pk_add_f32 v[108:109], v[108:109], 1.0 op_sel_hi:[1,0]
	s_nop 0
	v_rcp_f32_e32 v108, v108
	v_rcp_f32_e32 v109, v109
	v_pk_fma_f32 v[116:117], v[126:127], v[116:117], v[118:119]
	v_pk_mul_f32 v[96:97], v[96:97], v[108:109]
	v_pk_fma_f32 v[114:115], v[114:115], v[130:131], v[116:117]
	v_cndmask_b32_e64 v108, v193, v233, s[8:9]
	v_pk_mul_f32 v[96:97], v[114:115], v[96:97]
	v_cndmask_b32_e64 v114, v195, v235, s[6:7]
	v_cndmask_b32_e64 v115, v202, v239, s[6:7]
	v_cndmask_b32_e64 v109, v205, v241, s[8:9]
	v_pk_mul_f32 v[114:115], v[134:135], v[114:115]
	v_cndmask_b32_e64 v116, v198, v237, s[8:9]
	v_pk_fma_f32 v[108:109], v[138:139], v[108:109], v[114:115]
	v_cndmask_b32_e64 v114, v146, v207, s[6:7]
	v_pk_fma_f32 v[108:109], v[110:111], v[142:143], v[108:109]
	v_cndmask_b32_e64 v115, v150, v217, s[6:7]
	v_pk_mul_f32 v[110:111], v[108:109], s[40:41] op_sel_hi:[1,0]
	v_cndmask_b32_e64 v117, v147, v215, s[8:9]
	v_exp_f32_e32 v110, v110
	v_exp_f32_e32 v111, v111
	v_pk_mul_f32 v[114:115], v[122:123], v[114:115]
	v_pk_add_f32 v[110:111], v[110:111], 1.0 op_sel_hi:[1,0]
	s_nop 0
	v_rcp_f32_e32 v110, v110
	v_rcp_f32_e32 v111, v111
	v_pk_fma_f32 v[114:115], v[126:127], v[116:117], v[114:115]
	v_pk_mul_f32 v[108:109], v[108:109], v[110:111]
	v_pk_fma_f32 v[106:107], v[106:107], v[130:131], v[114:115]
	v_cndmask_b32_e64 v110, v225, v195, s[6:7]
	v_cndmask_b32_e64 v111, v229, v202, s[6:7]
	v_pk_mul_f32 v[106:107], v[106:107], v[108:109]
	v_cndmask_b32_e64 v108, v223, v193, s[8:9]
	v_cndmask_b32_e64 v109, v231, v205, s[8:9]
	v_pk_mul_f32 v[110:111], v[134:135], v[110:111]
	v_cndmask_b32_e64 v114, v227, v198, s[8:9]
	v_pk_fma_f32 v[108:109], v[138:139], v[108:109], v[110:111]
	v_cndmask_b32_e64 v110, v151, v146, s[6:7]
	v_pk_fma_f32 v[98:99], v[98:99], v[142:143], v[108:109]
	v_cndmask_b32_e64 v111, v203, v150, s[6:7]
;     __device__ __forceinline__ void operator()(const f32x4 (&acc)[2][2][4][2], const Unit& u, int wr, int wc, int fr, int fq) const {
;     ...
;         for (int n = 0; n < 2; ++n) {
;             if (n == 1) {
;                 asm volatile("" ::: "memory"); __builtin_amdgcn_sched_barrier(0);
; #pragma unroll
;                 for (int k = 0; k < 3; ++k) { wg[1][k] = *(const f32x4*)(cw + k * NUPc + j0 + 4); wv[1][k] = *(const f32x4*)(cw + k * NUPc + DFFc + j0 + 4); } }
; #pragma unroll
;             for (int ai = 0; ai < 2; ++ai) {
;                 __builtin_amdgcn_sched_barrier(0);
;                 const int jc = j0 + 4 * n;
;                 f32x2 o[4][2];
; #pragma unroll
;                 for (int xp = 0; xp < 2; ++xp) {
;                     const f32x2 a0 = (f32x2){wg[n][0][2 * xp], wg[n][0][2 * xp + 1]}, a1 = (f32x2){wg[n][1][2 * xp], wg[n][1][2 * xp + 1]}, a2 = (f32x2){wg[n][2][2 * xp], wg[n][2][2 * xp + 1]};
;                     const f32x2 b0 = (f32x2){wv[n][0][2 * xp], wv[n][0][2 * xp + 1]}, b1 = (f32x2){wv[n][1][2 * xp], wv[n][1][2 * xp + 1]}, b2 = (f32x2){wv[n][2][2 * xp], wv[n][2][2 * xp + 1]};
;                     f32x2 g1p = (f32x2){0.f, 0.f}, g2p = g1p, v1p = g1p, v2p = g1p;
; #pragma unroll
;                     for (int m = 0; m < 4; ++m) {
;                         const f32x2 g = (f32x2){acc[ai][0][m][n][2 * xp], acc[ai][0][m][n][2 * xp + 1]}, v = (f32x2){acc[ai][1][m][n][2 * xp], acc[ai][1][m][n][2 * xp + 1]};
;                         f32x2 g1, g2, v1, v2, ga, gb, va, vb;
; #pragma unroll
;                         for (int c = 0; c < 2; ++c) { g1[c] = dpp_ror<0x121>(g[c]); g2[c] = dpp_ror<0x122>(g[c]); v1[c] = dpp_ror<0x121>(v[c]); v2[c] = dpp_ror<0x122>(v[c]);
;                             ga[c] = fr == 0 ? g1p[c] : g1[c]; gb[c] = fr < 2 ? g2p[c] : g2[c]; va[c] = fr == 0 ? v1p[c] : v1[c]; vb[c] = fr < 2 ? v2p[c] : v2[c]; }
;                         const f32x2 G = a0 * gb + a1 * ga + a2 * g, V = b0 * vb + b1 * va + b2 * v;
;                         const f32x2 t = G * (-1.4426950408889634f);
;                         f32x2 e; e.x = __builtin_amdgcn_exp2f(t.x); e.y = __builtin_amdgcn_exp2f(t.y);
;                         const f32x2 dn = e + 1.0f;
;                         f32x2 rc; rc.x = __builtin_amdgcn_rcpf(dn.x); rc.y = __builtin_amdgcn_rcpf(dn.y);
;                         o[m][xp] = (G * rc) * V;
	v_pk_mul_f32 v[108:109], v[98:99], s[40:41] op_sel_hi:[1,0]
	v_cndmask_b32_e64 v115, v199, v147, s[8:9]
	v_exp_f32_e32 v108, v108
	v_exp_f32_e32 v109, v109
	v_pk_mul_f32 v[110:111], v[122:123], v[110:111]
	v_pk_add_f32 v[108:109], v[108:109], 1.0 op_sel_hi:[1,0]
	s_nop 0
	v_rcp_f32_e32 v108, v108
	v_rcp_f32_e32 v109, v109
	v_pk_fma_f32 v[110:111], v[126:127], v[114:115], v[110:111]
	v_pk_mul_f32 v[98:99], v[98:99], v[108:109]
	v_pk_fma_f32 v[102:103], v[102:103], v[130:131], v[110:111]
	v_mov_b64_e32 v[110:111], s[18:19]
	v_pk_mul_f32 v[108:109], v[102:103], v[98:99]
	v_cvt_pk_bf16_f32 v224, v112, v113
	v_cvt_pk_bf16_f32 v225, v96, v97
	v_or_b32_e32 v96, 16, v183
	v_mad_i64_i32 v[96:97], s[44:45], v96, s92, v[110:111]
	v_lshlrev_b64 v[102:103], 1, v[170:171]
	v_lshl_add_u64 v[96:97], v[96:97], 0, v[102:103]
	v_or_b32_e32 v98, 32, v183
	v_mad_i64_i32 v[98:99], s[44:45], v98, s92, v[110:111]
	v_cvt_pk_bf16_f32 v228, v104, v105
	v_lshl_add_u64 v[98:99], v[98:99], 0, v[102:103]
	v_cvt_pk_bf16_f32 v229, v106, v107
	v_cvt_pk_bf16_f32 v232, v100, v101
	v_or_b32_e32 v100, 48, v183
	v_mad_i64_i32 v[100:101], s[44:45], v100, s92, v[110:111]
	v_lshl_add_u64 v[100:101], v[100:101], 0, v[102:103]
	v_cvt_pk_bf16_f32 v233, v108, v109
	v_mov_b32_dpp v198, v92 row_ror:2 row_mask:0xf bank_mask:0xf
	s_nop 0
	v_mov_b32_dpp v206, v93 row_ror:2 row_mask:0xf bank_mask:0xf
	v_mov_b32_dpp v197, v92 row_ror:1 row_mask:0xf bank_mask:0xf
	v_cndmask_b32_e64 v106, v198, 0, s[6:7]
	v_mov_b32_dpp v209, v93 row_ror:1 row_mask:0xf bank_mask:0xf
	v_cndmask_b32_e64 v107, v206, 0, s[6:7]
	v_cndmask_b32_e64 v104, v197, 0, s[8:9]
	v_cndmask_b32_e64 v105, v209, 0, s[8:9]
	v_pk_mul_f32 v[106:107], v[132:133], v[106:107]
	s_nop 0
	v_pk_fma_f32 v[104:105], v[136:137], v[104:105], v[106:107]
	s_nop 0
	v_pk_fma_f32 v[92:93], v[92:93], v[140:141], v[104:105]
	s_nop 0
	v_pk_mul_f32 v[104:105], v[92:93], s[40:41] op_sel_hi:[1,0]
	s_nop 0
	v_mov_b32_dpp v110, v88 row_ror:2 row_mask:0xf bank_mask:0xf
	v_exp_f32_e32 v104, v104
	v_exp_f32_e32 v105, v105
	v_mov_b32_dpp v148, v89 row_ror:2 row_mask:0xf bank_mask:0xf
	v_mov_b32_dpp v144, v94 row_ror:2 row_mask:0xf bank_mask:0xf
	s_nop 0
	v_mov_b32_dpp v188, v95 row_ror:2 row_mask:0xf bank_mask:0xf
	v_cndmask_b32_e64 v112, v110, 0, s[6:7]
	v_cndmask_b32_e64 v113, v148, 0, s[6:7]
	v_mov_b32_dpp v118, v94 row_ror:1 row_mask:0xf bank_mask:0xf
	v_cndmask_b32_e64 v114, v144, 0, s[6:7]
	v_mov_b32_dpp v190, v95 row_ror:1 row_mask:0xf bank_mask:0xf
	v_cndmask_b32_e64 v115, v188, 0, s[6:7]
	v_pk_mul_f32 v[106:107], v[120:121], v[112:113]
	v_cndmask_b32_e64 v112, v118, 0, s[8:9]
	v_cndmask_b32_e64 v113, v190, 0, s[8:9]
	v_pk_mul_f32 v[114:115], v[134:135], v[114:115]
	v_pk_add_f32 v[104:105], v[104:105], 1.0 op_sel_hi:[1,0]
	v_pk_fma_f32 v[112:113], v[138:139], v[112:113], v[114:115]
	s_nop 0
	v_pk_fma_f32 v[94:95], v[94:95], v[142:143], v[112:113]
	s_nop 0
	v_rcp_f32_e32 v104, v104
	v_rcp_f32_e32 v105, v105
	v_pk_mul_f32 v[112:113], v[94:95], s[40:41] op_sel_hi:[1,0]
	v_mov_b32_dpp v200, v88 row_ror:1 row_mask:0xf bank_mask:0xf
	v_mov_b32_dpp v145, v89 row_ror:1 row_mask:0xf bank_mask:0xf
	v_exp_f32_e32 v112, v112
	v_exp_f32_e32 v113, v113
	v_cndmask_b32_e64 v108, v200, 0, s[8:9]
	v_cndmask_b32_e64 v109, v145, 0, s[8:9]
	v_pk_fma_f32 v[106:107], v[124:125], v[108:109], v[106:107]
	v_pk_mul_f32 v[92:93], v[92:93], v[104:105]
	v_pk_fma_f32 v[88:89], v[88:89], v[128:129], v[106:107]
	s_nop 0
	v_pk_mul_f32 v[88:89], v[88:89], v[92:93]
	s_nop 0
	v_pk_add_f32 v[112:113], v[112:113], 1.0 op_sel_hi:[1,0]
	s_nop 0
	v_mov_b32_dpp v93, v90 row_ror:2 row_mask:0xf bank_mask:0xf
	s_nop 0
	v_mov_b32_dpp v108, v91 row_ror:2 row_mask:0xf bank_mask:0xf
	v_rcp_f32_e32 v112, v112
	v_rcp_f32_e32 v113, v113
	v_mov_b32_dpp v146, v90 row_ror:1 row_mask:0xf bank_mask:0xf
	v_cndmask_b32_e64 v194, v93, 0, s[6:7]
	v_mov_b32_dpp v106, v91 row_ror:1 row_mask:0xf bank_mask:0xf
	v_cndmask_b32_e64 v195, v108, 0, s[6:7]
	v_cndmask_b32_e64 v116, v146, 0, s[8:9]
	v_cndmask_b32_e64 v117, v106, 0, s[8:9]
	v_pk_mul_f32 v[114:115], v[122:123], v[194:195]
	v_pk_mul_f32 v[94:95], v[94:95], v[112:113]
	v_pk_fma_f32 v[114:115], v[126:127], v[116:117], v[114:115]
	s_nop 0
	v_pk_fma_f32 v[90:91], v[90:91], v[130:131], v[114:115]
	s_nop 0
	s_nop 0
	s_nop 0
	v_pk_mul_f32 v[220:221], v[90:91], v[94:95]
	s_nop 0
	s_nop 0
	s_nop 0
	v_mov_b32_dpp v214, v84 row_ror:1 row_mask:0xf bank_mask:0xf
	v_mov_b32_dpp v215, v84 row_ror:2 row_mask:0xf bank_mask:0xf
	v_mov_b32_dpp v216, v80 row_ror:1 row_mask:0xf bank_mask:0xf
	v_mov_b32_dpp v192, v80 row_ror:2 row_mask:0xf bank_mask:0xf
	v_mov_b32_dpp v218, v85 row_ror:1 row_mask:0xf bank_mask:0xf
	v_mov_b32_dpp v217, v85 row_ror:2 row_mask:0xf bank_mask:0xf
	v_mov_b32_dpp v199, v81 row_ror:1 row_mask:0xf bank_mask:0xf
	v_mov_b32_dpp v201, v81 row_ror:2 row_mask:0xf bank_mask:0xf
	v_mov_b32_dpp v150, v76 row_ror:1 row_mask:0xf bank_mask:0xf
	v_mov_b32_dpp v151, v76 row_ror:2 row_mask:0xf bank_mask:0xf
	v_mov_b32_dpp v184, v72 row_ror:1 row_mask:0xf bank_mask:0xf
	v_mov_b32_dpp v104, v72 row_ror:2 row_mask:0xf bank_mask:0xf
	v_mov_b32_dpp v189, v77 row_ror:1 row_mask:0xf bank_mask:0xf
	v_mov_b32_dpp v186, v77 row_ror:2 row_mask:0xf bank_mask:0xf
	v_mov_b32_dpp v105, v73 row_ror:1 row_mask:0xf bank_mask:0xf
	v_mov_b32_dpp v107, v73 row_ror:2 row_mask:0xf bank_mask:0xf
	v_mov_b32_dpp v207, v68 row_ror:1 row_mask:0xf bank_mask:0xf
	v_mov_b32_dpp v210, v68 row_ror:2 row_mask:0xf bank_mask:0xf
	v_mov_b32_dpp v211, v64 row_ror:1 row_mask:0xf bank_mask:0xf
	v_mov_b32_dpp v119, v64 row_ror:2 row_mask:0xf bank_mask:0xf
	v_mov_b32_dpp v213, v69 row_ror:1 row_mask:0xf bank_mask:0xf
;     __device__ __forceinline__ void operator()(const f32x4 (&acc)[2][2][4][2], const Unit& u, int wr, int wc, int fr, int fq) const {
;     ...
;             for (int ai = 0; ai < 2; ++ai) {
;                 __builtin_amdgcn_sched_barrier(0);
;                 const int jc = j0 + 4 * n;
;                 f32x2 o[4][2];
; #pragma unroll
;                 for (int xp = 0; xp < 2; ++xp) {
;                     const f32x2 a0 = (f32x2){wg[n][0][2 * xp], wg[n][0][2 * xp + 1]}, a1 = (f32x2){wg[n][1][2 * xp], wg[n][1][2 * xp + 1]}, a2 = (f32x2){wg[n][2][2 * xp], wg[n][2][2 * xp + 1]};
;                     const f32x2 b0 = (f32x2){wv[n][0][2 * xp], wv[n][0][2 * xp + 1]}, b1 = (f32x2){wv[n][1][2 * xp], wv[n][1][2 * xp + 1]}, b2 = (f32x2){wv[n][2][2 * xp], wv[n][2][2 * xp + 1]};
;                     f32x2 g1p = (f32x2){0.f, 0.f}, g2p = g1p, v1p = g1p, v2p = g1p;
; #pragma unroll
;                     for (int m = 0; m < 4; ++m) {
;                         const f32x2 g = (f32x2){acc[ai][0][m][n][2 * xp], acc[ai][0][m][n][2 * xp + 1]}, v = (f32x2){acc[ai][1][m][n][2 * xp], acc[ai][1][m][n][2 * xp + 1]};
;                         f32x2 g1, g2, v1, v2, ga, gb, va, vb;
; #pragma unroll
;                         for (int c = 0; c < 2; ++c) { g1[c] = dpp_ror<0x121>(g[c]); g2[c] = dpp_ror<0x122>(g[c]); v1[c] = dpp_ror<0x121>(v[c]); v2[c] = dpp_ror<0x122>(v[c]);
;                             ga[c] = fr == 0 ? g1p[c] : g1[c]; gb[c] = fr < 2 ? g2p[c] : g2[c]; va[c] = fr == 0 ? v1p[c] : v1[c]; vb[c] = fr < 2 ? v2p[c] : v2[c]; }
;                         const f32x2 G = a0 * gb + a1 * ga + a2 * g, V = b0 * vb + b1 * va + b2 * v;
;                         const f32x2 t = G * (-1.4426950408889634f);
;                         f32x2 e; e.x = __builtin_amdgcn_exp2f(t.x); e.y = __builtin_amdgcn_exp2f(t.y);
;                         const f32x2 dn = e + 1.0f;
;                         f32x2 rc; rc.x = __builtin_amdgcn_rcpf(dn.x); rc.y = __builtin_amdgcn_rcpf(dn.y);
;                         o[m][xp] = (G * rc) * V;
;                         g1p = g1; g2p = g2; v1p = v1; v2p = v2;
;                     }
;                 }
; #pragma unroll
;                 for (int m = 0; m < 4; ++m) { const int row = u.pm * BM + ai * HALF + wr * 64 + m * 16 + fr;
;                     u32x2 w; w.x = cvt_pk_bf16(o[m][0].x, o[m][0].y); w.y = cvt_pk_bf16(o[m][1].x, o[m][1].y);
	v_mov_b32_dpp v212, v69 row_ror:2 row_mask:0xf bank_mask:0xf
	v_mov_b32_dpp v185, v65 row_ror:1 row_mask:0xf bank_mask:0xf
	v_mov_b32_dpp v187, v65 row_ror:2 row_mask:0xf bank_mask:0xf
	v_mov_b32_dpp v202, v86 row_ror:1 row_mask:0xf bank_mask:0xf
	v_mov_b32_dpp v203, v86 row_ror:2 row_mask:0xf bank_mask:0xf
	v_mov_b32_dpp v204, v82 row_ror:1 row_mask:0xf bank_mask:0xf
	v_mov_b32_dpp v117, v82 row_ror:2 row_mask:0xf bank_mask:0xf
	v_mov_b32_dpp v208, v87 row_ror:1 row_mask:0xf bank_mask:0xf
	v_mov_b32_dpp v205, v87 row_ror:2 row_mask:0xf bank_mask:0xf
	v_mov_b32_dpp v147, v83 row_ror:1 row_mask:0xf bank_mask:0xf
	v_mov_b32_dpp v149, v83 row_ror:2 row_mask:0xf bank_mask:0xf
	v_mov_b32_dpp v109, v78 row_ror:1 row_mask:0xf bank_mask:0xf
	v_mov_b32_dpp v111, v78 row_ror:2 row_mask:0xf bank_mask:0xf
	v_mov_b32_dpp v112, v74 row_ror:1 row_mask:0xf bank_mask:0xf
	v_mov_b32_dpp v90, v74 row_ror:2 row_mask:0xf bank_mask:0xf
	v_mov_b32_dpp v116, v79 row_ror:1 row_mask:0xf bank_mask:0xf
	v_mov_b32_dpp v114, v79 row_ror:2 row_mask:0xf bank_mask:0xf
	v_mov_b32_dpp v91, v75 row_ror:1 row_mask:0xf bank_mask:0xf
	v_mov_b32_dpp v92, v75 row_ror:2 row_mask:0xf bank_mask:0xf
	v_mov_b32_dpp v191, v70 row_ror:1 row_mask:0xf bank_mask:0xf
	v_mov_b32_dpp v193, v70 row_ror:2 row_mask:0xf bank_mask:0xf
	v_mov_b32_dpp v194, v66 row_ror:1 row_mask:0xf bank_mask:0xf
	v_mov_b32_dpp v95, v66 row_ror:2 row_mask:0xf bank_mask:0xf
	v_mov_b32_dpp v196, v71 row_ror:1 row_mask:0xf bank_mask:0xf
	v_mov_b32_dpp v195, v71 row_ror:2 row_mask:0xf bank_mask:0xf
	v_mov_b32_dpp v113, v67 row_ror:1 row_mask:0xf bank_mask:0xf
	v_mov_b32_dpp v115, v67 row_ror:2 row_mask:0xf bank_mask:0xf
	v_add_u32_e32 v94, 0x80, v183
	v_cvt_pk_bf16_f32 v236, v88, v89
	v_cvt_pk_bf16_f32 v237, v220, v221
	s_and_saveexec_b64 s[52:53], s[10:11]
	s_cbranch_execz .LBB0_680
	v_mov_b64_e32 v[220:221], s[18:19]
	v_mad_i64_i32 v[220:221], s[44:45], v94, s92, v[220:221]
	v_lshl_add_u64 v[220:221], v[170:171], 1, v[220:221]
.LBB0_680:
	s_or_b64 exec, exec, s[52:53]
	v_cndmask_b32_e64 v220, v215, v198, s[6:7]
	v_cndmask_b32_e64 v221, v217, v206, s[6:7]
	v_cndmask_b32_e64 v88, v214, v197, s[8:9]
	v_cndmask_b32_e64 v89, v218, v209, s[8:9]
	v_pk_mul_f32 v[220:221], v[132:133], v[220:221]
	v_cndmask_b32_e64 v222, v216, v200, s[8:9]
	v_pk_fma_f32 v[88:89], v[136:137], v[88:89], v[220:221]
	v_cndmask_b32_e64 v220, v192, v110, s[6:7]
	v_pk_fma_f32 v[84:85], v[84:85], v[140:141], v[88:89]
	v_cndmask_b32_e64 v221, v201, v148, s[6:7]
	v_pk_mul_f32 v[88:89], v[84:85], s[40:41] op_sel_hi:[1,0]
	v_cndmask_b32_e64 v223, v199, v145, s[8:9]
	v_exp_f32_e32 v88, v88
	v_exp_f32_e32 v89, v89
	v_pk_mul_f32 v[220:221], v[120:121], v[220:221]
	v_cndmask_b32_e64 v198, v184, v216, s[8:9]
	v_pk_fma_f32 v[220:221], v[124:125], v[222:223], v[220:221]
	v_pk_add_f32 v[88:89], v[88:89], 1.0 op_sel_hi:[1,0]
	v_pk_fma_f32 v[80:81], v[80:81], v[128:129], v[220:221]
	v_rcp_f32_e32 v88, v88
	v_rcp_f32_e32 v89, v89
	v_cndmask_b32_e64 v199, v105, v199, s[8:9]
	v_pk_mul_f32 v[84:85], v[84:85], v[88:89]
	v_cndmask_b32_e64 v88, v151, v215, s[6:7]
	v_cndmask_b32_e64 v89, v186, v217, s[6:7]
	v_pk_mul_f32 v[80:81], v[80:81], v[84:85]
	v_cndmask_b32_e64 v84, v150, v214, s[8:9]
	v_cndmask_b32_e64 v85, v189, v218, s[8:9]
	v_pk_mul_f32 v[88:89], v[132:133], v[88:89]
	s_nop 0
	v_pk_fma_f32 v[84:85], v[136:137], v[84:85], v[88:89]
	v_cndmask_b32_e64 v88, v104, v192, s[6:7]
	v_pk_fma_f32 v[76:77], v[76:77], v[140:141], v[84:85]
	v_cndmask_b32_e64 v89, v107, v201, s[6:7]
	v_pk_mul_f32 v[84:85], v[76:77], s[40:41] op_sel_hi:[1,0]
	v_pk_mul_f32 v[88:89], v[120:121], v[88:89]
	v_exp_f32_e32 v84, v84
	v_exp_f32_e32 v85, v85
	v_pk_fma_f32 v[88:89], v[124:125], v[198:199], v[88:89]
	v_pk_add_f32 v[84:85], v[84:85], 1.0 op_sel_hi:[1,0]
	s_nop 0
	v_rcp_f32_e32 v84, v84
	v_rcp_f32_e32 v85, v85
	v_pk_fma_f32 v[72:73], v[72:73], v[128:129], v[88:89]
	v_cndmask_b32_e64 v88, v211, v184, s[8:9]
	v_cndmask_b32_e64 v89, v185, v105, s[8:9]
	v_pk_mul_f32 v[76:77], v[76:77], v[84:85]
	v_cndmask_b32_e64 v84, v210, v151, s[6:7]
	v_cndmask_b32_e64 v85, v212, v186, s[6:7]
	v_pk_mul_f32 v[72:73], v[72:73], v[76:77]
	v_cndmask_b32_e64 v76, v207, v150, s[8:9]
	v_cndmask_b32_e64 v77, v213, v189, s[8:9]
	v_pk_mul_f32 v[84:85], v[132:133], v[84:85]
	s_nop 0
	v_pk_fma_f32 v[76:77], v[136:137], v[76:77], v[84:85]
	v_cndmask_b32_e64 v84, v119, v104, s[6:7]
	v_pk_fma_f32 v[68:69], v[68:69], v[140:141], v[76:77]
	v_cndmask_b32_e64 v85, v187, v107, s[6:7]
	v_pk_mul_f32 v[76:77], v[68:69], s[40:41] op_sel_hi:[1,0]
	v_pk_mul_f32 v[84:85], v[120:121], v[84:85]
	v_exp_f32_e32 v76, v76
	v_exp_f32_e32 v77, v77
	v_pk_fma_f32 v[84:85], v[124:125], v[88:89], v[84:85]
	v_pk_add_f32 v[76:77], v[76:77], 1.0 op_sel_hi:[1,0]
	s_nop 0
	v_rcp_f32_e32 v76, v76
	v_rcp_f32_e32 v77, v77
	v_pk_fma_f32 v[64:65], v[64:65], v[128:129], v[84:85]
	v_cndmask_b32_e64 v84, v204, v146, s[8:9]
	v_cndmask_b32_e64 v85, v147, v106, s[8:9]
	v_pk_mul_f32 v[68:69], v[68:69], v[76:77]
	v_cndmask_b32_e64 v76, v203, v144, s[6:7]
	v_cndmask_b32_e64 v77, v205, v188, s[6:7]
	v_pk_mul_f32 v[64:65], v[64:65], v[68:69]
	v_cndmask_b32_e64 v68, v202, v118, s[8:9]
	v_cndmask_b32_e64 v69, v208, v190, s[8:9]
	v_pk_mul_f32 v[76:77], v[134:135], v[76:77]
	s_nop 0
	v_pk_fma_f32 v[68:69], v[138:139], v[68:69], v[76:77]
	s_nop 0
	v_pk_fma_f32 v[68:69], v[86:87], v[142:143], v[68:69]
	v_cndmask_b32_e64 v86, v117, v93, s[6:7]
	v_pk_mul_f32 v[76:77], v[68:69], s[40:41] op_sel_hi:[1,0]
	v_cndmask_b32_e64 v87, v149, v108, s[6:7]
	v_exp_f32_e32 v76, v76
	v_exp_f32_e32 v77, v77
	v_pk_mul_f32 v[86:87], v[122:123], v[86:87]
	v_pk_add_f32 v[76:77], v[76:77], 1.0 op_sel_hi:[1,0]
;     __device__ __forceinline__ void operator()(const f32x4 (&acc)[2][2][4][2], const Unit& u, int wr, int wc, int fr, int fq) const {
;     ...
;         for (int n = 0; n < 2; ++n) {
;             if (n == 1) {
;                 asm volatile("" ::: "memory"); __builtin_amdgcn_sched_barrier(0);
; #pragma unroll
;                 for (int k = 0; k < 3; ++k) { wg[1][k] = *(const f32x4*)(cw + k * NUPc + j0 + 4); wv[1][k] = *(const f32x4*)(cw + k * NUPc + DFFc + j0 + 4); } }
; #pragma unroll
;             for (int ai = 0; ai < 2; ++ai) {
;                 __builtin_amdgcn_sched_barrier(0);
;                 const int jc = j0 + 4 * n;
;                 f32x2 o[4][2];
; #pragma unroll
;                 for (int xp = 0; xp < 2; ++xp) {
;                     const f32x2 a0 = (f32x2){wg[n][0][2 * xp], wg[n][0][2 * xp + 1]}, a1 = (f32x2){wg[n][1][2 * xp], wg[n][1][2 * xp + 1]}, a2 = (f32x2){wg[n][2][2 * xp], wg[n][2][2 * xp + 1]};
;                     const f32x2 b0 = (f32x2){wv[n][0][2 * xp], wv[n][0][2 * xp + 1]}, b1 = (f32x2){wv[n][1][2 * xp], wv[n][1][2 * xp + 1]}, b2 = (f32x2){wv[n][2][2 * xp], wv[n][2][2 * xp + 1]};
;                     f32x2 g1p = (f32x2){0.f, 0.f}, g2p = g1p, v1p = g1p, v2p = g1p;
; #pragma unroll
;                     for (int m = 0; m < 4; ++m) {
;                         const f32x2 g = (f32x2){acc[ai][0][m][n][2 * xp], acc[ai][0][m][n][2 * xp + 1]}, v = (f32x2){acc[ai][1][m][n][2 * xp], acc[ai][1][m][n][2 * xp + 1]};
;                         f32x2 g1, g2, v1, v2, ga, gb, va, vb;
; #pragma unroll
;                         for (int c = 0; c < 2; ++c) { g1[c] = dpp_ror<0x121>(g[c]); g2[c] = dpp_ror<0x122>(g[c]); v1[c] = dpp_ror<0x121>(v[c]); v2[c] = dpp_ror<0x122>(v[c]);
;                             ga[c] = fr == 0 ? g1p[c] : g1[c]; gb[c] = fr < 2 ? g2p[c] : g2[c]; va[c] = fr == 0 ? v1p[c] : v1[c]; vb[c] = fr < 2 ? v2p[c] : v2[c]; }
;                         const f32x2 G = a0 * gb + a1 * ga + a2 * g, V = b0 * vb + b1 * va + b2 * v;
;                         const f32x2 t = G * (-1.4426950408889634f);
;                         f32x2 e; e.x = __builtin_amdgcn_exp2f(t.x); e.y = __builtin_amdgcn_exp2f(t.y);
;                         const f32x2 dn = e + 1.0f;
;                         f32x2 rc; rc.x = __builtin_amdgcn_rcpf(dn.x); rc.y = __builtin_amdgcn_rcpf(dn.y);
;                         o[m][xp] = (G * rc) * V;
	s_nop 0
	v_rcp_f32_e32 v76, v76
	v_rcp_f32_e32 v77, v77
	v_pk_fma_f32 v[84:85], v[126:127], v[84:85], v[86:87]
	v_pk_mul_f32 v[68:69], v[68:69], v[76:77]
	v_pk_fma_f32 v[82:83], v[82:83], v[130:131], v[84:85]
	v_cndmask_b32_e64 v76, v109, v202, s[8:9]
	v_pk_mul_f32 v[68:69], v[82:83], v[68:69]
	v_cndmask_b32_e64 v82, v111, v203, s[6:7]
	v_cndmask_b32_e64 v83, v114, v205, s[6:7]
	v_cndmask_b32_e64 v77, v116, v208, s[8:9]
	v_pk_mul_f32 v[82:83], v[134:135], v[82:83]
	v_cndmask_b32_e64 v84, v112, v204, s[8:9]
	v_pk_fma_f32 v[76:77], v[138:139], v[76:77], v[82:83]
	v_cndmask_b32_e64 v82, v90, v117, s[6:7]
	v_pk_fma_f32 v[76:77], v[78:79], v[142:143], v[76:77]
	v_cndmask_b32_e64 v83, v92, v149, s[6:7]
	v_pk_mul_f32 v[78:79], v[76:77], s[40:41] op_sel_hi:[1,0]
	v_cndmask_b32_e64 v85, v91, v147, s[8:9]
	v_exp_f32_e32 v78, v78
	v_exp_f32_e32 v79, v79
	v_pk_mul_f32 v[82:83], v[122:123], v[82:83]
	v_pk_add_f32 v[78:79], v[78:79], 1.0 op_sel_hi:[1,0]
	s_nop 0
	v_rcp_f32_e32 v78, v78
	v_rcp_f32_e32 v79, v79
	v_pk_fma_f32 v[82:83], v[126:127], v[84:85], v[82:83]
	v_pk_mul_f32 v[76:77], v[76:77], v[78:79]
	v_pk_fma_f32 v[74:75], v[74:75], v[130:131], v[82:83]
	v_cndmask_b32_e64 v78, v193, v111, s[6:7]
	v_cndmask_b32_e64 v79, v195, v114, s[6:7]
	v_pk_mul_f32 v[74:75], v[74:75], v[76:77]
	v_cndmask_b32_e64 v76, v191, v109, s[8:9]
	v_cndmask_b32_e64 v77, v196, v116, s[8:9]
	v_pk_mul_f32 v[78:79], v[134:135], v[78:79]
	v_cndmask_b32_e64 v82, v194, v112, s[8:9]
	v_pk_fma_f32 v[76:77], v[138:139], v[76:77], v[78:79]
	v_cndmask_b32_e64 v78, v95, v90, s[6:7]
	v_pk_fma_f32 v[70:71], v[70:71], v[142:143], v[76:77]
	v_cndmask_b32_e64 v79, v115, v92, s[6:7]
	v_pk_mul_f32 v[76:77], v[70:71], s[40:41] op_sel_hi:[1,0]
	v_cndmask_b32_e64 v83, v113, v91, s[8:9]
	v_exp_f32_e32 v76, v76
	v_exp_f32_e32 v77, v77
	v_pk_mul_f32 v[78:79], v[122:123], v[78:79]
	v_pk_add_f32 v[76:77], v[76:77], 1.0 op_sel_hi:[1,0]
	s_nop 0
	v_rcp_f32_e32 v76, v76
	v_rcp_f32_e32 v77, v77
	v_pk_fma_f32 v[78:79], v[126:127], v[82:83], v[78:79]
	v_pk_mul_f32 v[70:71], v[70:71], v[76:77]
	v_pk_fma_f32 v[66:67], v[66:67], v[130:131], v[78:79]
	v_add_u32_e32 v76, 0x90, v183
	v_pk_mul_f32 v[66:67], v[66:67], v[70:71]
	v_cvt_pk_bf16_f32 v196, v80, v81
	v_cvt_pk_bf16_f32 v197, v68, v69
	v_mov_b64_e32 v[68:69], s[18:19]
	v_mad_i64_i32 v[76:77], s[44:45], v76, s92, v[68:69]
	v_lshl_add_u64 v[88:89], v[76:77], 0, v[102:103]
	v_cvt_pk_bf16_f32 v200, v72, v73
	v_add_u32_e32 v72, 0xa0, v183
	v_mad_i64_i32 v[72:73], s[44:45], v72, s92, v[68:69]
	v_lshl_add_u64 v[90:91], v[72:73], 0, v[102:103]
	v_cvt_pk_bf16_f32 v201, v74, v75
	v_cvt_pk_bf16_f32 v204, v64, v65
	v_cvt_pk_bf16_f32 v205, v66, v67
	v_add_u32_e32 v66, 0xb0, v183
	v_mad_i64_i32 v[66:67], s[44:45], v66, s92, v[68:69]
	v_lshl_add_u64 v[92:93], v[66:67], 0, v[102:103]
	s_mov_b32 s43, 0x1b000
	v_add_co_u32_e32 v64, vcc, s43, v172
	s_mov_b32 s43, 0x16000
	s_nop 0
	v_addc_co_u32_e32 v65, vcc, 0, v173, vcc
	v_add_co_u32_e32 v72, vcc, s93, v172
	global_load_dwordx4 v[64:67], v[64:65], off offset:2064
	s_nop 0
	global_load_dwordx4 v[68:71], v[172:173], off offset:16
	v_addc_co_u32_e32 v73, vcc, 0, v173, vcc
	v_add_co_u32_e32 v74, vcc, s43, v172
	s_mov_b32 s43, 0x10000
	s_nop 0
	v_addc_co_u32_e32 v75, vcc, 0, v173, vcc
	global_load_dwordx4 v[76:79], v[72:73], off offset:16
	global_load_dwordx4 v[80:83], v[74:75], off offset:16
	v_add_co_u32_e32 v72, vcc, s43, v172
	s_nop 1
	v_addc_co_u32_e32 v73, vcc, 0, v173, vcc
	v_add_co_u32_e32 v84, vcc, s94, v172
	s_nop 1
	v_addc_co_u32_e32 v85, vcc, 0, v173, vcc
	global_load_dwordx4 v[72:75], v[72:73], off offset:2064
	s_nop 0
	global_load_dwordx4 v[84:87], v[84:85], off offset:2064
	v_mov_b32_dpp v128, v60 row_ror:2 row_mask:0xf bank_mask:0xf
	s_nop 0
	v_mov_b32_dpp v136, v61 row_ror:2 row_mask:0xf bank_mask:0xf
	v_mov_b32_dpp v126, v60 row_ror:1 row_mask:0xf bank_mask:0xf
	v_cndmask_b32_e64 v110, v128, 0, s[6:7]
	v_mov_b32_dpp v140, v61 row_ror:1 row_mask:0xf bank_mask:0xf
	v_cndmask_b32_e64 v111, v136, 0, s[6:7]
	v_cndmask_b32_e64 v108, v126, 0, s[8:9]
	v_cndmask_b32_e64 v109, v140, 0, s[8:9]
	s_waitcnt vmcnt(4)
	v_pk_mul_f32 v[110:111], v[68:69], v[110:111]
	s_nop 0
	s_waitcnt vmcnt(3)
	v_pk_fma_f32 v[108:109], v[76:77], v[108:109], v[110:111]
	s_nop 0
	s_waitcnt vmcnt(2)
	v_pk_fma_f32 v[60:61], v[60:61], v[80:81], v[108:109]
	s_nop 0
	v_pk_mul_f32 v[108:109], v[60:61], s[40:41] op_sel_hi:[1,0]
	v_mov_b32_dpp v127, v62 row_ror:2 row_mask:0xf bank_mask:0xf
	s_nop 0
	v_mov_b32_dpp v135, v63 row_ror:2 row_mask:0xf bank_mask:0xf
	v_exp_f32_e32 v108, v108
	v_exp_f32_e32 v109, v109
	v_mov_b32_dpp v125, v62 row_ror:1 row_mask:0xf bank_mask:0xf
	v_cndmask_b32_e64 v190, v127, 0, s[6:7]
	v_mov_b32_dpp v138, v63 row_ror:1 row_mask:0xf bank_mask:0xf
	v_cndmask_b32_e64 v191, v135, 0, s[6:7]
	v_cndmask_b32_e64 v188, v125, 0, s[8:9]
	v_cndmask_b32_e64 v189, v138, 0, s[8:9]
	v_pk_mul_f32 v[190:191], v[70:71], v[190:191]
	v_pk_add_f32 v[108:109], v[108:109], 1.0 op_sel_hi:[1,0]
	v_pk_fma_f32 v[188:189], v[78:79], v[188:189], v[190:191]
	v_rcp_f32_e32 v108, v108
	v_pk_fma_f32 v[62:63], v[62:63], v[82:83], v[188:189]
	v_rcp_f32_e32 v109, v109
	v_pk_mul_f32 v[188:189], v[62:63], s[40:41] op_sel_hi:[1,0]
	s_nop 0
	v_exp_f32_e32 v188, v188
	v_exp_f32_e32 v189, v189
	v_pk_mul_f32 v[60:61], v[60:61], v[108:109]
	s_nop 0
	s_nop 0
	v_pk_add_f32 v[188:189], v[188:189], 1.0 op_sel_hi:[1,0]
	v_mov_b32_dpp v102, v56 row_ror:2 row_mask:0xf bank_mask:0xf
	v_mov_b32_dpp v107, v57 row_ror:2 row_mask:0xf bank_mask:0xf
	v_mov_b32_dpp v103, v58 row_ror:2 row_mask:0xf bank_mask:0xf
	v_mov_b32_dpp v108, v59 row_ror:2 row_mask:0xf bank_mask:0xf
	v_rcp_f32_e32 v188, v188
	v_rcp_f32_e32 v189, v189
	v_mov_b32_dpp v132, v56 row_ror:1 row_mask:0xf bank_mask:0xf
	v_cndmask_b32_e64 v114, v102, 0, s[6:7]
	v_mov_b32_dpp v105, v57 row_ror:1 row_mask:0xf bank_mask:0xf
	v_cndmask_b32_e64 v115, v107, 0, s[6:7]
	v_mov_b32_dpp v130, v58 row_ror:1 row_mask:0xf bank_mask:0xf
	v_cndmask_b32_e64 v194, v103, 0, s[6:7]
	v_mov_b32_dpp v106, v59 row_ror:1 row_mask:0xf bank_mask:0xf
	v_cndmask_b32_e64 v195, v108, 0, s[6:7]
	v_cndmask_b32_e64 v112, v132, 0, s[8:9]
	v_cndmask_b32_e64 v113, v105, 0, s[8:9]
	s_waitcnt vmcnt(0)
;     __device__ __forceinline__ void operator()(const f32x4 (&acc)[2][2][4][2], const Unit& u, int wr, int wc, int fr, int fq) const {
;     ...
;             for (int ai = 0; ai < 2; ++ai) {
;                 __builtin_amdgcn_sched_barrier(0);
;                 const int jc = j0 + 4 * n;
;                 f32x2 o[4][2];
; #pragma unroll
;                 for (int xp = 0; xp < 2; ++xp) {
;                     const f32x2 a0 = (f32x2){wg[n][0][2 * xp], wg[n][0][2 * xp + 1]}, a1 = (f32x2){wg[n][1][2 * xp], wg[n][1][2 * xp + 1]}, a2 = (f32x2){wg[n][2][2 * xp], wg[n][2][2 * xp + 1]};
;                     const f32x2 b0 = (f32x2){wv[n][0][2 * xp], wv[n][0][2 * xp + 1]}, b1 = (f32x2){wv[n][1][2 * xp], wv[n][1][2 * xp + 1]}, b2 = (f32x2){wv[n][2][2 * xp], wv[n][2][2 * xp + 1]};
;                     f32x2 g1p = (f32x2){0.f, 0.f}, g2p = g1p, v1p = g1p, v2p = g1p;
; #pragma unroll
;                     for (int m = 0; m < 4; ++m) {
;                         const f32x2 g = (f32x2){acc[ai][0][m][n][2 * xp], acc[ai][0][m][n][2 * xp + 1]}, v = (f32x2){acc[ai][1][m][n][2 * xp], acc[ai][1][m][n][2 * xp + 1]};
;                         f32x2 g1, g2, v1, v2, ga, gb, va, vb;
; #pragma unroll
;                         for (int c = 0; c < 2; ++c) { g1[c] = dpp_ror<0x121>(g[c]); g2[c] = dpp_ror<0x122>(g[c]); v1[c] = dpp_ror<0x121>(v[c]); v2[c] = dpp_ror<0x122>(v[c]);
;                             ga[c] = fr == 0 ? g1p[c] : g1[c]; gb[c] = fr < 2 ? g2p[c] : g2[c]; va[c] = fr == 0 ? v1p[c] : v1[c]; vb[c] = fr < 2 ? v2p[c] : v2[c]; }
;                         const f32x2 G = a0 * gb + a1 * ga + a2 * g, V = b0 * vb + b1 * va + b2 * v;
;                         const f32x2 t = G * (-1.4426950408889634f);
;                         f32x2 e; e.x = __builtin_amdgcn_exp2f(t.x); e.y = __builtin_amdgcn_exp2f(t.y);
;                         const f32x2 dn = e + 1.0f;
;                         f32x2 rc; rc.x = __builtin_amdgcn_rcpf(dn.x); rc.y = __builtin_amdgcn_rcpf(dn.y);
;                         o[m][xp] = (G * rc) * V;
;                         g1p = g1; g2p = g2; v1p = v1; v2p = v2;
;                     }
;                 }
; #pragma unroll
;                 for (int m = 0; m < 4; ++m) { const int row = u.pm * BM + ai * HALF + wr * 64 + m * 16 + fr;
;                     u32x2 w; w.x = cvt_pk_bf16(o[m][0].x, o[m][0].y); w.y = cvt_pk_bf16(o[m][1].x, o[m][1].y);
	v_pk_mul_f32 v[110:111], v[84:85], v[114:115]
	v_cndmask_b32_e64 v192, v130, 0, s[8:9]
	v_cndmask_b32_e64 v193, v106, 0, s[8:9]
	v_pk_mul_f32 v[190:191], v[86:87], v[194:195]
	v_pk_fma_f32 v[110:111], v[72:73], v[112:113], v[110:111]
	v_pk_fma_f32 v[190:191], v[74:75], v[192:193], v[190:191]
	v_pk_fma_f32 v[56:57], v[56:57], v[64:65], v[110:111]
	v_pk_fma_f32 v[58:59], v[58:59], v[66:67], v[190:191]
	v_pk_mul_f32 v[62:63], v[62:63], v[188:189]
	v_pk_mul_f32 v[56:57], v[56:57], v[60:61]
	s_nop 0
	s_nop 0
	s_nop 0
	v_pk_mul_f32 v[190:191], v[58:59], v[62:63]
	s_nop 0
	s_nop 0
	s_nop 0
	v_mov_b32_dpp v149, v52 row_ror:1 row_mask:0xf bank_mask:0xf
	v_mov_b32_dpp v151, v52 row_ror:2 row_mask:0xf bank_mask:0xf
	v_mov_b32_dpp v173, v48 row_ror:1 row_mask:0xf bank_mask:0xf
	v_mov_b32_dpp v123, v48 row_ror:2 row_mask:0xf bank_mask:0xf
	v_mov_b32_dpp v187, v53 row_ror:1 row_mask:0xf bank_mask:0xf
	v_mov_b32_dpp v185, v53 row_ror:2 row_mask:0xf bank_mask:0xf
	v_mov_b32_dpp v129, v49 row_ror:1 row_mask:0xf bank_mask:0xf
	v_mov_b32_dpp v133, v49 row_ror:2 row_mask:0xf bank_mask:0xf
	v_mov_b32_dpp v109, v44 row_ror:1 row_mask:0xf bank_mask:0xf
	v_mov_b32_dpp v111, v44 row_ror:2 row_mask:0xf bank_mask:0xf
	v_mov_b32_dpp v113, v40 row_ror:1 row_mask:0xf bank_mask:0xf
	v_mov_b32_dpp v60, v40 row_ror:2 row_mask:0xf bank_mask:0xf
	v_mov_b32_dpp v121, v45 row_ror:1 row_mask:0xf bank_mask:0xf
	v_mov_b32_dpp v117, v45 row_ror:2 row_mask:0xf bank_mask:0xf
	v_mov_b32_dpp v61, v41 row_ror:1 row_mask:0xf bank_mask:0xf
	v_mov_b32_dpp v95, v41 row_ror:2 row_mask:0xf bank_mask:0xf
	v_mov_b32_dpp v137, v36 row_ror:1 row_mask:0xf bank_mask:0xf
	v_mov_b32_dpp v141, v36 row_ror:2 row_mask:0xf bank_mask:0xf
	v_mov_b32_dpp v143, v32 row_ror:1 row_mask:0xf bank_mask:0xf
	v_mov_b32_dpp v104, v32 row_ror:2 row_mask:0xf bank_mask:0xf
	v_mov_b32_dpp v147, v37 row_ror:1 row_mask:0xf bank_mask:0xf
	v_mov_b32_dpp v145, v37 row_ror:2 row_mask:0xf bank_mask:0xf
	v_mov_b32_dpp v114, v33 row_ror:1 row_mask:0xf bank_mask:0xf
	v_mov_b32_dpp v118, v33 row_ror:2 row_mask:0xf bank_mask:0xf
	v_mov_b32_dpp v150, v54 row_ror:1 row_mask:0xf bank_mask:0xf
	v_mov_b32_dpp v172, v54 row_ror:2 row_mask:0xf bank_mask:0xf
	v_mov_b32_dpp v184, v50 row_ror:1 row_mask:0xf bank_mask:0xf
	v_mov_b32_dpp v124, v50 row_ror:2 row_mask:0xf bank_mask:0xf
	v_mov_b32_dpp v188, v55 row_ror:1 row_mask:0xf bank_mask:0xf
	v_mov_b32_dpp v186, v55 row_ror:2 row_mask:0xf bank_mask:0xf
	v_mov_b32_dpp v131, v51 row_ror:1 row_mask:0xf bank_mask:0xf
	v_mov_b32_dpp v134, v51 row_ror:2 row_mask:0xf bank_mask:0xf
	v_mov_b32_dpp v110, v46 row_ror:1 row_mask:0xf bank_mask:0xf
	v_mov_b32_dpp v112, v46 row_ror:2 row_mask:0xf bank_mask:0xf
	v_mov_b32_dpp v115, v42 row_ror:1 row_mask:0xf bank_mask:0xf
	v_mov_b32_dpp v58, v42 row_ror:2 row_mask:0xf bank_mask:0xf
	v_mov_b32_dpp v122, v47 row_ror:1 row_mask:0xf bank_mask:0xf
	v_mov_b32_dpp v119, v47 row_ror:2 row_mask:0xf bank_mask:0xf
	v_mov_b32_dpp v59, v43 row_ror:1 row_mask:0xf bank_mask:0xf
	v_mov_b32_dpp v62, v43 row_ror:2 row_mask:0xf bank_mask:0xf
	v_mov_b32_dpp v139, v38 row_ror:1 row_mask:0xf bank_mask:0xf
	v_mov_b32_dpp v142, v38 row_ror:2 row_mask:0xf bank_mask:0xf
	v_mov_b32_dpp v144, v34 row_ror:1 row_mask:0xf bank_mask:0xf
	v_mov_b32_dpp v63, v34 row_ror:2 row_mask:0xf bank_mask:0xf
	v_mov_b32_dpp v148, v39 row_ror:1 row_mask:0xf bank_mask:0xf
	v_mov_b32_dpp v146, v39 row_ror:2 row_mask:0xf bank_mask:0xf
	v_mov_b32_dpp v116, v35 row_ror:1 row_mask:0xf bank_mask:0xf
	v_mov_b32_dpp v120, v35 row_ror:2 row_mask:0xf bank_mask:0xf
	v_cvt_pk_bf16_f32 v56, v56, v57
	v_cvt_pk_bf16_f32 v57, v190, v191
	s_and_saveexec_b64 s[52:53], s[10:11]
	s_cbranch_execz .LBB0_682
	v_mov_b64_e32 v[190:191], s[18:19]
	v_mad_i64_i32 v[190:191], s[44:45], v183, s92, v[190:191]
	v_lshl_add_u64 v[190:191], v[170:171], 1, v[190:191]
	global_store_dwordx2 v[190:191], v[56:57], off offset:8
.LBB0_682:
	s_or_b64 exec, exec, s[52:53]
	v_cndmask_b32_e64 v190, v151, v128, s[6:7]
	v_cndmask_b32_e64 v191, v185, v136, s[6:7]
	v_cndmask_b32_e64 v56, v149, v126, s[8:9]
	v_cndmask_b32_e64 v57, v187, v140, s[8:9]
	v_pk_mul_f32 v[190:191], v[68:69], v[190:191]
	v_cndmask_b32_e64 v192, v173, v132, s[8:9]
	v_pk_fma_f32 v[56:57], v[76:77], v[56:57], v[190:191]
	v_cndmask_b32_e64 v190, v123, v102, s[6:7]
	v_pk_fma_f32 v[52:53], v[52:53], v[80:81], v[56:57]
	v_cndmask_b32_e64 v191, v133, v107, s[6:7]
	v_pk_mul_f32 v[56:57], v[52:53], s[40:41] op_sel_hi:[1,0]
	v_cndmask_b32_e64 v193, v129, v105, s[8:9]
	v_exp_f32_e32 v56, v56
	v_exp_f32_e32 v57, v57
	v_pk_mul_f32 v[190:191], v[84:85], v[190:191]
	v_cndmask_b32_e64 v128, v113, v173, s[8:9]
	v_pk_fma_f32 v[190:191], v[72:73], v[192:193], v[190:191]
	v_pk_add_f32 v[56:57], v[56:57], 1.0 op_sel_hi:[1,0]
	v_pk_fma_f32 v[48:49], v[48:49], v[64:65], v[190:191]
	v_rcp_f32_e32 v56, v56
	v_rcp_f32_e32 v57, v57
	v_cndmask_b32_e64 v129, v61, v129, s[8:9]
	v_pk_mul_f32 v[52:53], v[52:53], v[56:57]
	v_cndmask_b32_e64 v56, v111, v151, s[6:7]
	v_cndmask_b32_e64 v57, v117, v185, s[6:7]
	v_pk_mul_f32 v[48:49], v[48:49], v[52:53]
	v_cndmask_b32_e64 v52, v109, v149, s[8:9]
	v_cndmask_b32_e64 v53, v121, v187, s[8:9]
	v_pk_mul_f32 v[56:57], v[68:69], v[56:57]
	s_nop 0
	v_pk_fma_f32 v[52:53], v[76:77], v[52:53], v[56:57]
	v_cndmask_b32_e64 v56, v60, v123, s[6:7]
	v_pk_fma_f32 v[44:45], v[44:45], v[80:81], v[52:53]
	v_cndmask_b32_e64 v57, v95, v133, s[6:7]
	v_pk_mul_f32 v[52:53], v[44:45], s[40:41] op_sel_hi:[1,0]
	v_pk_mul_f32 v[56:57], v[84:85], v[56:57]
	v_exp_f32_e32 v52, v52
	v_exp_f32_e32 v53, v53
	v_pk_fma_f32 v[56:57], v[72:73], v[128:129], v[56:57]
	v_pk_add_f32 v[52:53], v[52:53], 1.0 op_sel_hi:[1,0]
;     __device__ __forceinline__ void operator()(const f32x4 (&acc)[2][2][4][2], const Unit& u, int wr, int wc, int fr, int fq) const {
;     ...
;             for (int ai = 0; ai < 2; ++ai) {
;                 __builtin_amdgcn_sched_barrier(0);
;                 const int jc = j0 + 4 * n;
;                 f32x2 o[4][2];
; #pragma unroll
;                 for (int xp = 0; xp < 2; ++xp) {
;                     const f32x2 a0 = (f32x2){wg[n][0][2 * xp], wg[n][0][2 * xp + 1]}, a1 = (f32x2){wg[n][1][2 * xp], wg[n][1][2 * xp + 1]}, a2 = (f32x2){wg[n][2][2 * xp], wg[n][2][2 * xp + 1]};
;                     const f32x2 b0 = (f32x2){wv[n][0][2 * xp], wv[n][0][2 * xp + 1]}, b1 = (f32x2){wv[n][1][2 * xp], wv[n][1][2 * xp + 1]}, b2 = (f32x2){wv[n][2][2 * xp], wv[n][2][2 * xp + 1]};
;                     f32x2 g1p = (f32x2){0.f, 0.f}, g2p = g1p, v1p = g1p, v2p = g1p;
; #pragma unroll
;                     for (int m = 0; m < 4; ++m) {
;                         const f32x2 g = (f32x2){acc[ai][0][m][n][2 * xp], acc[ai][0][m][n][2 * xp + 1]}, v = (f32x2){acc[ai][1][m][n][2 * xp], acc[ai][1][m][n][2 * xp + 1]};
;                         f32x2 g1, g2, v1, v2, ga, gb, va, vb;
; #pragma unroll
;                         for (int c = 0; c < 2; ++c) { g1[c] = dpp_ror<0x121>(g[c]); g2[c] = dpp_ror<0x122>(g[c]); v1[c] = dpp_ror<0x121>(v[c]); v2[c] = dpp_ror<0x122>(v[c]);
;                             ga[c] = fr == 0 ? g1p[c] : g1[c]; gb[c] = fr < 2 ? g2p[c] : g2[c]; va[c] = fr == 0 ? v1p[c] : v1[c]; vb[c] = fr < 2 ? v2p[c] : v2[c]; }
;                         const f32x2 G = a0 * gb + a1 * ga + a2 * g, V = b0 * vb + b1 * va + b2 * v;
;                         const f32x2 t = G * (-1.4426950408889634f);
;                         f32x2 e; e.x = __builtin_amdgcn_exp2f(t.x); e.y = __builtin_amdgcn_exp2f(t.y);
;                         const f32x2 dn = e + 1.0f;
;                         f32x2 rc; rc.x = __builtin_amdgcn_rcpf(dn.x); rc.y = __builtin_amdgcn_rcpf(dn.y);
;                         o[m][xp] = (G * rc) * V;
;                         g1p = g1; g2p = g2; v1p = v1; v2p = v2;
;                     }
;                 }
; #pragma unroll
;                 for (int m = 0; m < 4; ++m) { const int row = u.pm * BM + ai * HALF + wr * 64 + m * 16 + fr;
;                     u32x2 w; w.x = cvt_pk_bf16(o[m][0].x, o[m][0].y); w.y = cvt_pk_bf16(o[m][1].x, o[m][1].y);
	s_nop 0
	v_rcp_f32_e32 v52, v52
	v_rcp_f32_e32 v53, v53
	v_pk_fma_f32 v[40:41], v[40:41], v[64:65], v[56:57]
	v_cndmask_b32_e64 v56, v143, v113, s[8:9]
	v_cndmask_b32_e64 v57, v114, v61, s[8:9]
	v_pk_mul_f32 v[44:45], v[44:45], v[52:53]
	v_cndmask_b32_e64 v52, v141, v111, s[6:7]
	v_cndmask_b32_e64 v53, v145, v117, s[6:7]
	v_pk_mul_f32 v[40:41], v[40:41], v[44:45]
	v_cndmask_b32_e64 v44, v137, v109, s[8:9]
	v_cndmask_b32_e64 v45, v147, v121, s[8:9]
	v_pk_mul_f32 v[52:53], v[68:69], v[52:53]
	s_nop 0
	v_pk_fma_f32 v[44:45], v[76:77], v[44:45], v[52:53]
	v_cndmask_b32_e64 v52, v104, v60, s[6:7]
	v_pk_fma_f32 v[36:37], v[36:37], v[80:81], v[44:45]
	v_cndmask_b32_e64 v53, v118, v95, s[6:7]
	v_pk_mul_f32 v[44:45], v[36:37], s[40:41] op_sel_hi:[1,0]
	v_pk_mul_f32 v[52:53], v[84:85], v[52:53]
	v_exp_f32_e32 v44, v44
	v_exp_f32_e32 v45, v45
	v_pk_fma_f32 v[52:53], v[72:73], v[56:57], v[52:53]
	v_pk_add_f32 v[44:45], v[44:45], 1.0 op_sel_hi:[1,0]
	s_nop 0
	v_rcp_f32_e32 v44, v44
	v_rcp_f32_e32 v45, v45
	v_pk_fma_f32 v[32:33], v[32:33], v[64:65], v[52:53]
	v_cndmask_b32_e64 v52, v184, v130, s[8:9]
	v_cndmask_b32_e64 v53, v131, v106, s[8:9]
	v_pk_mul_f32 v[36:37], v[36:37], v[44:45]
	v_cndmask_b32_e64 v44, v172, v127, s[6:7]
	v_cndmask_b32_e64 v45, v186, v135, s[6:7]
	v_pk_mul_f32 v[32:33], v[32:33], v[36:37]
	v_cndmask_b32_e64 v36, v150, v125, s[8:9]
	v_cndmask_b32_e64 v37, v188, v138, s[8:9]
	v_pk_mul_f32 v[44:45], v[70:71], v[44:45]
	s_nop 0
	v_pk_fma_f32 v[36:37], v[78:79], v[36:37], v[44:45]
	s_nop 0
	v_pk_fma_f32 v[36:37], v[54:55], v[82:83], v[36:37]
	v_cndmask_b32_e64 v54, v124, v103, s[6:7]
	v_pk_mul_f32 v[44:45], v[36:37], s[40:41] op_sel_hi:[1,0]
	v_cndmask_b32_e64 v55, v134, v108, s[6:7]
	v_exp_f32_e32 v44, v44
	v_exp_f32_e32 v45, v45
	v_pk_mul_f32 v[54:55], v[86:87], v[54:55]
	v_pk_add_f32 v[44:45], v[44:45], 1.0 op_sel_hi:[1,0]
	s_nop 0
	v_rcp_f32_e32 v44, v44
	v_rcp_f32_e32 v45, v45
	v_pk_fma_f32 v[52:53], v[74:75], v[52:53], v[54:55]
	v_pk_mul_f32 v[36:37], v[36:37], v[44:45]
	v_pk_fma_f32 v[50:51], v[50:51], v[66:67], v[52:53]
	v_cndmask_b32_e64 v44, v110, v150, s[8:9]
	v_pk_mul_f32 v[36:37], v[50:51], v[36:37]
	v_cndmask_b32_e64 v50, v112, v172, s[6:7]
	v_cndmask_b32_e64 v51, v119, v186, s[6:7]
	v_cndmask_b32_e64 v45, v122, v188, s[8:9]
	v_pk_mul_f32 v[50:51], v[70:71], v[50:51]
	v_cndmask_b32_e64 v52, v115, v184, s[8:9]
	v_pk_fma_f32 v[44:45], v[78:79], v[44:45], v[50:51]
	v_cndmask_b32_e64 v50, v58, v124, s[6:7]
	v_pk_fma_f32 v[44:45], v[46:47], v[82:83], v[44:45]
	v_cndmask_b32_e64 v51, v62, v134, s[6:7]
	v_pk_mul_f32 v[46:47], v[44:45], s[40:41] op_sel_hi:[1,0]
	v_cndmask_b32_e64 v53, v59, v131, s[8:9]
	v_exp_f32_e32 v46, v46
	v_exp_f32_e32 v47, v47
	v_pk_mul_f32 v[50:51], v[86:87], v[50:51]
	v_pk_add_f32 v[46:47], v[46:47], 1.0 op_sel_hi:[1,0]
	s_nop 0
	v_rcp_f32_e32 v46, v46
	v_rcp_f32_e32 v47, v47
	v_pk_fma_f32 v[50:51], v[74:75], v[52:53], v[50:51]
	v_pk_mul_f32 v[44:45], v[44:45], v[46:47]
	v_pk_fma_f32 v[42:43], v[42:43], v[66:67], v[50:51]
	v_cndmask_b32_e64 v46, v142, v112, s[6:7]
	v_cndmask_b32_e64 v47, v146, v119, s[6:7]
	v_pk_mul_f32 v[42:43], v[42:43], v[44:45]
	v_cndmask_b32_e64 v44, v139, v110, s[8:9]
	v_cndmask_b32_e64 v45, v148, v122, s[8:9]
	v_pk_mul_f32 v[46:47], v[70:71], v[46:47]
	v_cndmask_b32_e64 v50, v144, v115, s[8:9]
	v_pk_fma_f32 v[44:45], v[78:79], v[44:45], v[46:47]
	v_cndmask_b32_e64 v46, v63, v58, s[6:7]
	v_pk_fma_f32 v[38:39], v[38:39], v[82:83], v[44:45]
	v_cndmask_b32_e64 v47, v120, v62, s[6:7]
	v_pk_mul_f32 v[44:45], v[38:39], s[40:41] op_sel_hi:[1,0]
	v_cndmask_b32_e64 v51, v116, v59, s[8:9]
	v_exp_f32_e32 v44, v44
	v_exp_f32_e32 v45, v45
	v_pk_mul_f32 v[46:47], v[86:87], v[46:47]
	v_pk_add_f32 v[44:45], v[44:45], 1.0 op_sel_hi:[1,0]
	s_nop 0
	v_rcp_f32_e32 v44, v44
	v_rcp_f32_e32 v45, v45
	v_pk_fma_f32 v[46:47], v[74:75], v[50:51], v[46:47]
	v_pk_mul_f32 v[38:39], v[38:39], v[44:45]
	v_pk_fma_f32 v[34:35], v[34:35], v[66:67], v[46:47]
	s_nop 0
	v_pk_mul_f32 v[34:35], v[34:35], v[38:39]
	v_cvt_pk_bf16_f32 v226, v48, v49
	v_cvt_pk_bf16_f32 v227, v36, v37
	global_store_dwordx4 v[96:97], v[224:227], off
	v_cvt_pk_bf16_f32 v230, v40, v41
	v_cvt_pk_bf16_f32 v231, v42, v43
	global_store_dwordx4 v[98:99], v[228:231], off
	v_cvt_pk_bf16_f32 v234, v32, v33
	v_cvt_pk_bf16_f32 v235, v34, v35
	global_store_dwordx4 v[100:101], v[232:235], off
	s_nop 0
	s_nop 0
	s_nop 0
	v_mov_b32_dpp v33, v28 row_ror:2 row_mask:0xf bank_mask:0xf
	v_mov_b32_dpp v37, v29 row_ror:2 row_mask:0xf bank_mask:0xf
	v_mov_b32_dpp v63, v30 row_ror:2 row_mask:0xf bank_mask:0xf
	s_nop 0
	v_mov_b32_dpp v98, v31 row_ror:2 row_mask:0xf bank_mask:0xf
	v_mov_b32_dpp v34, v28 row_ror:1 row_mask:0xf bank_mask:0xf
	v_cndmask_b32_e64 v42, v33, 0, s[6:7]
	v_mov_b32_dpp v38, v29 row_ror:1 row_mask:0xf bank_mask:0xf
	v_cndmask_b32_e64 v43, v37, 0, s[6:7]
	v_mov_b32_dpp v95, v30 row_ror:1 row_mask:0xf bank_mask:0xf
	v_cndmask_b32_e64 v104, v63, 0, s[6:7]
	v_mov_b32_dpp v99, v31 row_ror:1 row_mask:0xf bank_mask:0xf
	v_cndmask_b32_e64 v105, v98, 0, s[6:7]
	v_cndmask_b32_e64 v40, v34, 0, s[8:9]
	v_cndmask_b32_e64 v41, v38, 0, s[8:9]
	v_pk_mul_f32 v[42:43], v[68:69], v[42:43]
	v_cndmask_b32_e64 v102, v95, 0, s[8:9]
	v_cndmask_b32_e64 v103, v99, 0, s[8:9]
	v_pk_mul_f32 v[104:105], v[70:71], v[104:105]
	v_pk_fma_f32 v[40:41], v[76:77], v[40:41], v[42:43]
	v_pk_fma_f32 v[102:103], v[78:79], v[102:103], v[104:105]
	v_pk_fma_f32 v[28:29], v[28:29], v[80:81], v[40:41]
	v_pk_fma_f32 v[30:31], v[30:31], v[82:83], v[102:103]
	v_pk_mul_f32 v[40:41], v[28:29], s[40:41] op_sel_hi:[1,0]
	v_pk_mul_f32 v[102:103], v[30:31], s[40:41] op_sel_hi:[1,0]
	v_exp_f32_e32 v40, v40
;     __device__ __forceinline__ void operator()(const f32x4 (&acc)[2][2][4][2], const Unit& u, int wr, int wc, int fr, int fq) const {
;     ...
;             for (int ai = 0; ai < 2; ++ai) {
;                 __builtin_amdgcn_sched_barrier(0);
;                 const int jc = j0 + 4 * n;
;                 f32x2 o[4][2];
; #pragma unroll
;                 for (int xp = 0; xp < 2; ++xp) {
;                     const f32x2 a0 = (f32x2){wg[n][0][2 * xp], wg[n][0][2 * xp + 1]}, a1 = (f32x2){wg[n][1][2 * xp], wg[n][1][2 * xp + 1]}, a2 = (f32x2){wg[n][2][2 * xp], wg[n][2][2 * xp + 1]};
;                     const f32x2 b0 = (f32x2){wv[n][0][2 * xp], wv[n][0][2 * xp + 1]}, b1 = (f32x2){wv[n][1][2 * xp], wv[n][1][2 * xp + 1]}, b2 = (f32x2){wv[n][2][2 * xp], wv[n][2][2 * xp + 1]};
;                     f32x2 g1p = (f32x2){0.f, 0.f}, g2p = g1p, v1p = g1p, v2p = g1p;
; #pragma unroll
;                     for (int m = 0; m < 4; ++m) {
;                         const f32x2 g = (f32x2){acc[ai][0][m][n][2 * xp], acc[ai][0][m][n][2 * xp + 1]}, v = (f32x2){acc[ai][1][m][n][2 * xp], acc[ai][1][m][n][2 * xp + 1]};
;                         f32x2 g1, g2, v1, v2, ga, gb, va, vb;
; #pragma unroll
;                         for (int c = 0; c < 2; ++c) { g1[c] = dpp_ror<0x121>(g[c]); g2[c] = dpp_ror<0x122>(g[c]); v1[c] = dpp_ror<0x121>(v[c]); v2[c] = dpp_ror<0x122>(v[c]);
;                             ga[c] = fr == 0 ? g1p[c] : g1[c]; gb[c] = fr < 2 ? g2p[c] : g2[c]; va[c] = fr == 0 ? v1p[c] : v1[c]; vb[c] = fr < 2 ? v2p[c] : v2[c]; }
;                         const f32x2 G = a0 * gb + a1 * ga + a2 * g, V = b0 * vb + b1 * va + b2 * v;
;                         const f32x2 t = G * (-1.4426950408889634f);
;                         f32x2 e; e.x = __builtin_amdgcn_exp2f(t.x); e.y = __builtin_amdgcn_exp2f(t.y);
;                         const f32x2 dn = e + 1.0f;
;                         f32x2 rc; rc.x = __builtin_amdgcn_rcpf(dn.x); rc.y = __builtin_amdgcn_rcpf(dn.y);
;                         o[m][xp] = (G * rc) * V;
;                         g1p = g1; g2p = g2; v1p = v1; v2p = v2;
;                     }
;                 }
; #pragma unroll
;                 for (int m = 0; m < 4; ++m) { const int row = u.pm * BM + ai * HALF + wr * 64 + m * 16 + fr;
;                     u32x2 w; w.x = cvt_pk_bf16(o[m][0].x, o[m][0].y); w.y = cvt_pk_bf16(o[m][1].x, o[m][1].y);
	v_exp_f32_e32 v41, v41
	v_exp_f32_e32 v102, v102
	v_exp_f32_e32 v103, v103
	s_nop 0
	v_pk_add_f32 v[40:41], v[40:41], 1.0 op_sel_hi:[1,0]
	s_nop 0
	v_pk_add_f32 v[102:103], v[102:103], 1.0 op_sel_hi:[1,0]
	v_mov_b32_dpp v32, v24 row_ror:2 row_mask:0xf bank_mask:0xf
	v_mov_b32_dpp v36, v25 row_ror:2 row_mask:0xf bank_mask:0xf
	v_rcp_f32_e32 v40, v40
	v_rcp_f32_e32 v41, v41
	v_mov_b32_dpp v62, v26 row_ror:2 row_mask:0xf bank_mask:0xf
	v_mov_b32_dpp v97, v27 row_ror:2 row_mask:0xf bank_mask:0xf
	v_rcp_f32_e32 v102, v102
	v_rcp_f32_e32 v103, v103
	v_mov_b32_dpp v39, v24 row_ror:1 row_mask:0xf bank_mask:0xf
	v_cndmask_b32_e64 v46, v32, 0, s[6:7]
	v_mov_b32_dpp v35, v25 row_ror:1 row_mask:0xf bank_mask:0xf
	v_cndmask_b32_e64 v47, v36, 0, s[6:7]
	v_mov_b32_dpp v100, v26 row_ror:1 row_mask:0xf bank_mask:0xf
	v_cndmask_b32_e64 v108, v62, 0, s[6:7]
	v_mov_b32_dpp v96, v27 row_ror:1 row_mask:0xf bank_mask:0xf
	v_cndmask_b32_e64 v109, v97, 0, s[6:7]
	v_cndmask_b32_e64 v44, v39, 0, s[8:9]
	v_cndmask_b32_e64 v45, v35, 0, s[8:9]
	v_pk_mul_f32 v[42:43], v[84:85], v[46:47]
	v_cndmask_b32_e64 v106, v100, 0, s[8:9]
	v_cndmask_b32_e64 v107, v96, 0, s[8:9]
	v_pk_mul_f32 v[104:105], v[86:87], v[108:109]
	v_pk_fma_f32 v[42:43], v[72:73], v[44:45], v[42:43]
	v_pk_fma_f32 v[104:105], v[74:75], v[106:107], v[104:105]
	v_pk_fma_f32 v[24:25], v[24:25], v[64:65], v[42:43]
	v_pk_mul_f32 v[28:29], v[28:29], v[40:41]
	v_pk_fma_f32 v[26:27], v[26:27], v[66:67], v[104:105]
	v_pk_mul_f32 v[30:31], v[30:31], v[102:103]
	v_pk_mul_f32 v[24:25], v[24:25], v[28:29]
	s_nop 0
	s_nop 0
	s_nop 0
	v_pk_mul_f32 v[122:123], v[26:27], v[30:31]
	s_nop 0
	s_nop 0
	s_nop 0
	v_mov_b32_dpp v42, v8 row_ror:1 row_mask:0xf bank_mask:0xf
	v_mov_b32_dpp v29, v8 row_ror:2 row_mask:0xf bank_mask:0xf
	v_mov_b32_dpp v45, v0 row_ror:1 row_mask:0xf bank_mask:0xf
	v_mov_b32_dpp v28, v0 row_ror:2 row_mask:0xf bank_mask:0xf
	v_mov_b32_dpp v44, v9 row_ror:1 row_mask:0xf bank_mask:0xf
	v_mov_b32_dpp v43, v9 row_ror:2 row_mask:0xf bank_mask:0xf
	v_mov_b32_dpp v40, v1 row_ror:1 row_mask:0xf bank_mask:0xf
	v_mov_b32_dpp v41, v1 row_ror:2 row_mask:0xf bank_mask:0xf
	v_mov_b32_dpp v50, v20 row_ror:1 row_mask:0xf bank_mask:0xf
	v_mov_b32_dpp v47, v20 row_ror:2 row_mask:0xf bank_mask:0xf
	v_mov_b32_dpp v53, v4 row_ror:1 row_mask:0xf bank_mask:0xf
	v_mov_b32_dpp v46, v4 row_ror:2 row_mask:0xf bank_mask:0xf
	v_mov_b32_dpp v52, v21 row_ror:1 row_mask:0xf bank_mask:0xf
	v_mov_b32_dpp v51, v21 row_ror:2 row_mask:0xf bank_mask:0xf
	v_mov_b32_dpp v48, v5 row_ror:1 row_mask:0xf bank_mask:0xf
	v_mov_b32_dpp v49, v5 row_ror:2 row_mask:0xf bank_mask:0xf
	v_mov_b32_dpp v58, v16 row_ror:1 row_mask:0xf bank_mask:0xf
	v_mov_b32_dpp v55, v16 row_ror:2 row_mask:0xf bank_mask:0xf
	v_mov_b32_dpp v61, v12 row_ror:1 row_mask:0xf bank_mask:0xf
	v_mov_b32_dpp v54, v12 row_ror:2 row_mask:0xf bank_mask:0xf
	v_mov_b32_dpp v60, v17 row_ror:1 row_mask:0xf bank_mask:0xf
	v_mov_b32_dpp v59, v17 row_ror:2 row_mask:0xf bank_mask:0xf
	v_mov_b32_dpp v56, v13 row_ror:1 row_mask:0xf bank_mask:0xf
	v_mov_b32_dpp v57, v13 row_ror:2 row_mask:0xf bank_mask:0xf
	v_mov_b32_dpp v101, v10 row_ror:1 row_mask:0xf bank_mask:0xf
	v_mov_b32_dpp v27, v10 row_ror:2 row_mask:0xf bank_mask:0xf
	v_mov_b32_dpp v104, v2 row_ror:1 row_mask:0xf bank_mask:0xf
	v_mov_b32_dpp v26, v2 row_ror:2 row_mask:0xf bank_mask:0xf
	v_mov_b32_dpp v103, v11 row_ror:1 row_mask:0xf bank_mask:0xf
	v_mov_b32_dpp v102, v11 row_ror:2 row_mask:0xf bank_mask:0xf
	v_mov_b32_dpp v30, v3 row_ror:1 row_mask:0xf bank_mask:0xf
	v_mov_b32_dpp v31, v3 row_ror:2 row_mask:0xf bank_mask:0xf
	v_mov_b32_dpp v109, v22 row_ror:1 row_mask:0xf bank_mask:0xf
	v_mov_b32_dpp v106, v22 row_ror:2 row_mask:0xf bank_mask:0xf
	v_mov_b32_dpp v112, v6 row_ror:1 row_mask:0xf bank_mask:0xf
	v_mov_b32_dpp v105, v6 row_ror:2 row_mask:0xf bank_mask:0xf
	v_mov_b32_dpp v111, v23 row_ror:1 row_mask:0xf bank_mask:0xf
	v_mov_b32_dpp v110, v23 row_ror:2 row_mask:0xf bank_mask:0xf
	v_mov_b32_dpp v107, v7 row_ror:1 row_mask:0xf bank_mask:0xf
	v_mov_b32_dpp v108, v7 row_ror:2 row_mask:0xf bank_mask:0xf
	v_mov_b32_dpp v117, v18 row_ror:1 row_mask:0xf bank_mask:0xf
	v_mov_b32_dpp v116, v18 row_ror:2 row_mask:0xf bank_mask:0xf
	v_mov_b32_dpp v120, v14 row_ror:1 row_mask:0xf bank_mask:0xf
	v_mov_b32_dpp v113, v14 row_ror:2 row_mask:0xf bank_mask:0xf
	v_mov_b32_dpp v119, v19 row_ror:1 row_mask:0xf bank_mask:0xf
	v_mov_b32_dpp v118, v19 row_ror:2 row_mask:0xf bank_mask:0xf
	v_mov_b32_dpp v114, v15 row_ror:1 row_mask:0xf bank_mask:0xf
	v_mov_b32_dpp v115, v15 row_ror:2 row_mask:0xf bank_mask:0xf
	v_cvt_pk_bf16_f32 v238, v24, v25
	v_cvt_pk_bf16_f32 v239, v122, v123
	s_and_saveexec_b64 s[52:53], s[10:11]
	s_cbranch_execz .LBB0_684
	v_mov_b64_e32 v[122:123], s[18:19]
	v_mad_i64_i32 v[122:123], s[44:45], v94, s92, v[122:123]
	v_lshl_add_u64 v[122:123], v[170:171], 1, v[122:123]
	global_store_dwordx4 v[122:123], v[236:239], off
;     __device__ __forceinline__ void operator()(const f32x4 (&acc)[2][2][4][2], const Unit& u, int wr, int wc, int fr, int fq) const {
;     ...
;             for (int ai = 0; ai < 2; ++ai) {
;                 __builtin_amdgcn_sched_barrier(0);
;                 const int jc = j0 + 4 * n;
;                 f32x2 o[4][2];
; #pragma unroll
;                 for (int xp = 0; xp < 2; ++xp) {
;                     const f32x2 a0 = (f32x2){wg[n][0][2 * xp], wg[n][0][2 * xp + 1]}, a1 = (f32x2){wg[n][1][2 * xp], wg[n][1][2 * xp + 1]}, a2 = (f32x2){wg[n][2][2 * xp], wg[n][2][2 * xp + 1]};
;                     const f32x2 b0 = (f32x2){wv[n][0][2 * xp], wv[n][0][2 * xp + 1]}, b1 = (f32x2){wv[n][1][2 * xp], wv[n][1][2 * xp + 1]}, b2 = (f32x2){wv[n][2][2 * xp], wv[n][2][2 * xp + 1]};
;                     f32x2 g1p = (f32x2){0.f, 0.f}, g2p = g1p, v1p = g1p, v2p = g1p;
; #pragma unroll
;                     for (int m = 0; m < 4; ++m) {
;                         const f32x2 g = (f32x2){acc[ai][0][m][n][2 * xp], acc[ai][0][m][n][2 * xp + 1]}, v = (f32x2){acc[ai][1][m][n][2 * xp], acc[ai][1][m][n][2 * xp + 1]};
;                         f32x2 g1, g2, v1, v2, ga, gb, va, vb;
; #pragma unroll
;                         for (int c = 0; c < 2; ++c) { g1[c] = dpp_ror<0x121>(g[c]); g2[c] = dpp_ror<0x122>(g[c]); v1[c] = dpp_ror<0x121>(v[c]); v2[c] = dpp_ror<0x122>(v[c]);
;                             ga[c] = fr == 0 ? g1p[c] : g1[c]; gb[c] = fr < 2 ? g2p[c] : g2[c]; va[c] = fr == 0 ? v1p[c] : v1[c]; vb[c] = fr < 2 ? v2p[c] : v2[c]; }
;                         const f32x2 G = a0 * gb + a1 * ga + a2 * g, V = b0 * vb + b1 * va + b2 * v;
;                         const f32x2 t = G * (-1.4426950408889634f);
;                         f32x2 e; e.x = __builtin_amdgcn_exp2f(t.x); e.y = __builtin_amdgcn_exp2f(t.y);
;                         const f32x2 dn = e + 1.0f;
;                         f32x2 rc; rc.x = __builtin_amdgcn_rcpf(dn.x); rc.y = __builtin_amdgcn_rcpf(dn.y);
;                         o[m][xp] = (G * rc) * V;
;                         g1p = g1; g2p = g2; v1p = v1; v2p = v2;
;                     }
;                 }
; #pragma unroll
;                 for (int m = 0; m < 4; ++m) { const int row = u.pm * BM + ai * HALF + wr * 64 + m * 16 + fr;
;                     u32x2 w; w.x = cvt_pk_bf16(o[m][0].x, o[m][0].y); w.y = cvt_pk_bf16(o[m][1].x, o[m][1].y);
.LBB0_684:
	s_or_b64 exec, exec, s[52:53]
	v_cndmask_b32_e64 v24, v120, v112, s[8:9]
	v_cndmask_b32_e64 v120, v117, v109, s[8:9]
	v_cndmask_b32_e64 v116, v116, v106, s[6:7]
	v_cndmask_b32_e64 v117, v118, v110, s[6:7]
	v_cndmask_b32_e64 v121, v119, v111, s[8:9]
	v_pk_mul_f32 v[116:117], v[70:71], v[116:117]
	v_cndmask_b32_e64 v25, v114, v107, s[8:9]
	v_pk_fma_f32 v[116:117], v[78:79], v[120:121], v[116:117]
	v_cndmask_b32_e64 v114, v113, v105, s[6:7]
	v_pk_fma_f32 v[18:19], v[18:19], v[82:83], v[116:117]
	v_cndmask_b32_e64 v115, v115, v108, s[6:7]
	v_pk_mul_f32 v[116:117], v[18:19], s[40:41] op_sel_hi:[1,0]
	v_pk_mul_f32 v[114:115], v[86:87], v[114:115]
	v_exp_f32_e32 v116, v116
	v_exp_f32_e32 v117, v117
	v_pk_fma_f32 v[24:25], v[74:75], v[24:25], v[114:115]
	v_cndmask_b32_e64 v113, v110, v102, s[6:7]
	v_pk_fma_f32 v[14:15], v[14:15], v[66:67], v[24:25]
	v_pk_add_f32 v[116:117], v[116:117], 1.0 op_sel_hi:[1,0]
	v_cndmask_b32_e64 v24, v109, v101, s[8:9]
	v_rcp_f32_e32 v116, v116
	v_rcp_f32_e32 v117, v117
	v_cndmask_b32_e64 v25, v111, v103, s[8:9]
	s_andn2_b64 vcc, exec, s[12:13]
	s_mov_b64 s[12:13], -1
	v_pk_mul_f32 v[18:19], v[18:19], v[116:117]
	s_nop 0
	v_pk_mul_f32 v[14:15], v[14:15], v[18:19]
	v_cndmask_b32_e64 v18, v112, v104, s[8:9]
	v_cndmask_b32_e64 v112, v106, v27, s[6:7]
	v_pk_mul_f32 v[110:111], v[70:71], v[112:113]
	v_cndmask_b32_e64 v19, v107, v30, s[8:9]
	v_pk_fma_f32 v[24:25], v[78:79], v[24:25], v[110:111]
	v_cndmask_b32_e64 v106, v105, v26, s[6:7]
	v_pk_fma_f32 v[22:23], v[22:23], v[82:83], v[24:25]
	v_cndmask_b32_e64 v107, v108, v31, s[6:7]
	v_pk_mul_f32 v[24:25], v[22:23], s[40:41] op_sel_hi:[1,0]
	v_pk_mul_f32 v[106:107], v[86:87], v[106:107]
	v_exp_f32_e32 v24, v24
	v_exp_f32_e32 v25, v25
	v_pk_fma_f32 v[18:19], v[74:75], v[18:19], v[106:107]
	v_pk_add_f32 v[24:25], v[24:25], 1.0 op_sel_hi:[1,0]
	s_nop 0
	v_rcp_f32_e32 v24, v24
	v_rcp_f32_e32 v25, v25
	v_pk_fma_f32 v[6:7], v[6:7], v[66:67], v[18:19]
	v_pk_mul_f32 v[18:19], v[22:23], v[24:25]
	v_cndmask_b32_e64 v24, v27, v63, s[6:7]
	v_cndmask_b32_e64 v25, v102, v98, s[6:7]
	v_cndmask_b32_e64 v22, v101, v95, s[8:9]
	v_cndmask_b32_e64 v23, v103, v99, s[8:9]
	v_pk_mul_f32 v[24:25], v[70:71], v[24:25]
	v_pk_mul_f32 v[6:7], v[6:7], v[18:19]
	v_pk_fma_f32 v[22:23], v[78:79], v[22:23], v[24:25]
	v_cndmask_b32_e64 v24, v26, v62, s[6:7]
	v_pk_fma_f32 v[10:11], v[10:11], v[82:83], v[22:23]
	v_cndmask_b32_e64 v25, v31, v97, s[6:7]
	v_pk_mul_f32 v[22:23], v[10:11], s[40:41] op_sel_hi:[1,0]
	v_cndmask_b32_e64 v18, v104, v100, s[8:9]
	v_exp_f32_e32 v22, v22
	v_exp_f32_e32 v23, v23
	v_cndmask_b32_e64 v19, v30, v96, s[8:9]
	v_pk_mul_f32 v[24:25], v[86:87], v[24:25]
	v_pk_add_f32 v[22:23], v[22:23], 1.0 op_sel_hi:[1,0]
	s_nop 0
	v_rcp_f32_e32 v22, v22
	v_rcp_f32_e32 v23, v23
	v_pk_fma_f32 v[18:19], v[74:75], v[18:19], v[24:25]
	v_pk_mul_f32 v[10:11], v[10:11], v[22:23]
	v_cndmask_b32_e64 v22, v55, v47, s[6:7]
	v_cndmask_b32_e64 v23, v59, v51, s[6:7]
	v_pk_fma_f32 v[2:3], v[2:3], v[66:67], v[18:19]
	v_cndmask_b32_e64 v18, v58, v50, s[8:9]
	v_cndmask_b32_e64 v19, v60, v52, s[8:9]
	v_pk_mul_f32 v[22:23], v[68:69], v[22:23]
	v_pk_mul_f32 v[2:3], v[2:3], v[10:11]
	v_pk_fma_f32 v[18:19], v[76:77], v[18:19], v[22:23]
	v_cndmask_b32_e64 v22, v54, v46, s[6:7]
	v_pk_fma_f32 v[16:17], v[16:17], v[80:81], v[18:19]
	v_cndmask_b32_e64 v23, v57, v49, s[6:7]
	v_pk_mul_f32 v[18:19], v[16:17], s[40:41] op_sel_hi:[1,0]
	v_cndmask_b32_e64 v10, v61, v53, s[8:9]
	v_exp_f32_e32 v18, v18
	v_exp_f32_e32 v19, v19
	v_cndmask_b32_e64 v11, v56, v48, s[8:9]
	v_pk_mul_f32 v[22:23], v[84:85], v[22:23]
	v_pk_add_f32 v[18:19], v[18:19], 1.0 op_sel_hi:[1,0]
	s_nop 0
	v_rcp_f32_e32 v18, v18
	v_rcp_f32_e32 v19, v19
	v_pk_fma_f32 v[10:11], v[72:73], v[10:11], v[22:23]
	s_nop 0
	v_pk_fma_f32 v[10:11], v[12:13], v[64:65], v[10:11]
	v_pk_mul_f32 v[12:13], v[16:17], v[18:19]
	v_cndmask_b32_e64 v18, v47, v29, s[6:7]
	v_cndmask_b32_e64 v19, v51, v43, s[6:7]
	v_cndmask_b32_e64 v16, v50, v42, s[8:9]
	v_cndmask_b32_e64 v17, v52, v44, s[8:9]
	v_pk_mul_f32 v[18:19], v[68:69], v[18:19]
	v_pk_mul_f32 v[10:11], v[10:11], v[12:13]
	v_pk_fma_f32 v[16:17], v[76:77], v[16:17], v[18:19]
	v_cndmask_b32_e64 v12, v53, v45, s[8:9]
	v_pk_fma_f32 v[16:17], v[20:21], v[80:81], v[16:17]
	v_cndmask_b32_e64 v20, v46, v28, s[6:7]
	v_pk_mul_f32 v[18:19], v[16:17], s[40:41] op_sel_hi:[1,0]
	v_cndmask_b32_e64 v21, v49, v41, s[6:7]
	v_exp_f32_e32 v18, v18
	v_exp_f32_e32 v19, v19
	v_cndmask_b32_e64 v13, v48, v40, s[8:9]
	v_pk_mul_f32 v[20:21], v[84:85], v[20:21]
	v_pk_add_f32 v[18:19], v[18:19], 1.0 op_sel_hi:[1,0]
	s_nop 0
	v_rcp_f32_e32 v18, v18
	v_rcp_f32_e32 v19, v19
	v_pk_fma_f32 v[12:13], v[72:73], v[12:13], v[20:21]
	s_nop 0
	v_pk_fma_f32 v[4:5], v[4:5], v[64:65], v[12:13]
	v_pk_mul_f32 v[12:13], v[16:17], v[18:19]
	v_cndmask_b32_e64 v18, v29, v33, s[6:7]
	v_cndmask_b32_e64 v19, v43, v37, s[6:7]
	v_cndmask_b32_e64 v16, v42, v34, s[8:9]
	v_cndmask_b32_e64 v17, v44, v38, s[8:9]
	v_pk_mul_f32 v[18:19], v[68:69], v[18:19]
	v_pk_mul_f32 v[4:5], v[4:5], v[12:13]
	v_pk_fma_f32 v[16:17], v[76:77], v[16:17], v[18:19]
	v_cndmask_b32_e64 v18, v28, v32, s[6:7]
	v_pk_fma_f32 v[8:9], v[8:9], v[80:81], v[16:17]
	v_cndmask_b32_e64 v19, v41, v36, s[6:7]
	v_pk_mul_f32 v[16:17], v[8:9], s[40:41] op_sel_hi:[1,0]
	v_cndmask_b32_e64 v12, v45, v39, s[8:9]
	v_exp_f32_e32 v16, v16
	v_exp_f32_e32 v17, v17
	v_cndmask_b32_e64 v13, v40, v35, s[8:9]
	v_pk_mul_f32 v[18:19], v[84:85], v[18:19]
	v_pk_add_f32 v[16:17], v[16:17], 1.0 op_sel_hi:[1,0]
	s_nop 0
	v_rcp_f32_e32 v16, v16
	v_rcp_f32_e32 v17, v17
	v_pk_fma_f32 v[12:13], v[72:73], v[12:13], v[18:19]
	v_pk_mul_f32 v[8:9], v[8:9], v[16:17]
	v_pk_fma_f32 v[0:1], v[0:1], v[64:65], v[12:13]
	s_nop 0
	v_pk_mul_f32 v[0:1], v[0:1], v[8:9]
	s_nop 0
	v_cvt_pk_bf16_f32 v198, v0, v1
	v_cvt_pk_bf16_f32 v199, v2, v3
	global_store_dwordx4 v[88:89], v[196:199], off
	v_cvt_pk_bf16_f32 v202, v4, v5
	v_cvt_pk_bf16_f32 v203, v6, v7
	global_store_dwordx4 v[90:91], v[200:203], off
	v_cvt_pk_bf16_f32 v206, v10, v11
	v_cvt_pk_bf16_f32 v207, v14, v15
	global_store_dwordx4 v[92:93], v[204:207], off
	s_cbranch_vccnz .LBB0_667
	s_andn2_b64 vcc, exec, s[16:17]
	s_cbranch_vccnz .LBB0_666
	s_barrier
	s_branch .LBB0_666
